# GEMM loops without any s_setprio (A/B of the per-phase priority flips)
# speedup vs baseline: 1.0110x; 1.0044x over previous
; #define PG8_STAGE(bufoff, gbase, voff) do { _Pragma("unroll") for (int _i = 0; _i < 2; ++_i) \
;         __builtin_amdgcn_global_load_lds((const unsigned*)((const char*)(gbase) + (voff)[_i]), (LAS unsigned*)(lds + (bufoff) + ldsw + _i * 8192), 16, 0, 0); } while (0)
; #define PG8_LDA(dst, b, h) do { _Pragma("unroll") for (int m = 0; m < 4; ++m) _Pragma("unroll") for (int k = 0; k < 2; ++k) dst[m][k] = *(const LAS bf16x8*)(lds + PG8_SA(b, h) + aoff + m * 2048 + k * 1024); } while (0)
; #define PG8_LDB(dst, b, h) do { _Pragma("unroll") for (int n = 0; n < 2; ++n) _Pragma("unroll") for (int k = 0; k < 2; ++k) dst[n][k] = *(const LAS bf16x8*)(lds + PG8_SB(b, h) + boff + n * 2048 + k * 1024); } while (0)
; #define PG8_MMA(ai, bj, At, Bt) do { __builtin_amdgcn_s_setprio(1); _Pragma("unroll") for (int m = 0; m < 4; ++m) _Pragma("unroll") for (int n = 0; n < 2; ++n) _Pragma("unroll") for (int k = 0; k < 2; ++k) \
;         acc[ai][bj][m][n] = __builtin_amdgcn_mfma_f32_16x16x32_bf16(Bt[n][k], At[m][k], acc[ai][bj][m][n], 0, 0, 0); __builtin_amdgcn_s_setprio(0); } while (0)
; #define PG8_WAIT_V(n) asm volatile("s_waitcnt vmcnt(" #n ")" ::: "memory")
; #define PG8_WAIT_L(n) asm volatile("s_waitcnt lgkmcnt(" #n ")" ::: "memory")
; #define PG8_BAR __builtin_amdgcn_s_barrier()
; #define PG8_SCHED __builtin_amdgcn_sched_barrier(0)
; __device__ __forceinline__ void gemm_phase(LAS unsigned char* lds, const Params& p, const bf16_t* gA, const bf16_t* gBt, const int gM, const int gN, const int gK, const int epi, const int perm, bf16_t* const Hp, const int goff, const float coef) {
;     ...
;         for (int t = 0; t < nt; t += 2) {
;             const bool last = (t == nt - 2);
;             const char* a1 = cA + (size_t)(t + 1) * kstep;
;             const char* a2 = last ? nA : cA + (size_t)(t + 2) * kstep; const char* b2 = last ? nB : cB + (size_t)(t + 2) * kstep;
;             const char* a3 = a2 + kstep; const char* b3 = b2 + kstep;
;             PG8_LDB(B0, 0, 0); PG8_LDB(B1, 0, 1); PG8_SCHED; PG8_LDA(At, 0, 0); PG8_STAGE(PG8_SA(1, 1), a1 + hstep, voffA);
;             PG8_WAIT_V(8); PG8_WAIT_L(0); PG8_BAR; PG8_MMA(0, 0, At, B0); PG8_MMA(0, 1, At, B1); PG8_BAR; PG8_SCHED;
;             PG8_LDA(At, 0, 1); PG8_STAGE(PG8_SB(0, 0), b2, voffB); PG8_STAGE(PG8_SB(0, 1), b2 + hstep, voffB); PG8_STAGE(PG8_SA(0, 0), a2, voffA);
.LBB0_170:
	ds_read_b128 v[158:161], v155
	ds_read_b128 v[162:165], v155 offset:1024
	ds_read_b128 v[166:169], v155 offset:2048
	ds_read_b128 v[170:173], v155 offset:3072
	ds_read_b128 v[174:177], v156
	ds_read_b128 v[178:181], v156 offset:1024
	ds_read_b128 v[182:185], v156 offset:2048
	ds_read_b128 v[186:189], v156 offset:3072
	s_add_i32 s56, s48, 2
	s_add_u32 s46, s44, 0xfff80080
	s_addc_u32 s47, s45, -1
	s_cmp_eq_u32 s53, s48
	s_cselect_b32 s48, s50, s46
	s_cselect_b32 s49, s25, s47
	s_cselect_b32 s47, s27, s55
	s_cselect_b32 s46, s51, s54
	v_lshl_add_u64 v[144:145], s[44:45], 0, v[136:137]
	s_add_i32 m0, s14, 0xc000
	ds_read_b128 v[190:193], v157
	ds_read_b128 v[194:197], v157 offset:1024
	ds_read_b128 v[198:201], v157 offset:2048
	ds_read_b128 v[202:205], v157 offset:3072
	ds_read_b128 v[206:209], v157 offset:4096
	ds_read_b128 v[210:213], v157 offset:5120
	ds_read_b128 v[214:217], v157 offset:6144
	ds_read_b128 v[218:221], v157 offset:7168
	global_load_lds_dwordx4 v[144:145], off
	v_lshl_add_u64 v[144:145], s[44:45], 0, v[138:139]
	s_add_i32 m0, s14, 0xe000
	s_nop 0
	global_load_lds_dwordx4 v[144:145], off
	s_waitcnt vmcnt(8)
	s_waitcnt lgkmcnt(0)
	s_barrier
	s_waitcnt lgkmcnt(0)
	v_mfma_f32_16x16x32_bf16 v[124:127], v[158:161], v[190:193], v[124:127]
	v_mfma_f32_16x16x32_bf16 v[120:123], v[166:169], v[190:193], v[120:123]
	v_mfma_f32_16x16x32_bf16 v[108:111], v[158:161], v[198:201], v[108:111]
	v_mfma_f32_16x16x32_bf16 v[104:107], v[166:169], v[198:201], v[104:107]
	v_mfma_f32_16x16x32_bf16 v[92:95], v[158:161], v[206:209], v[92:95]
	v_mfma_f32_16x16x32_bf16 v[88:91], v[166:169], v[206:209], v[88:91]
	v_mfma_f32_16x16x32_bf16 v[76:79], v[158:161], v[214:217], v[76:79]
	v_mfma_f32_16x16x32_bf16 v[72:75], v[166:169], v[214:217], v[72:75]
	v_mfma_f32_16x16x32_bf16 v[124:127], v[162:165], v[194:197], v[124:127]
	v_mfma_f32_16x16x32_bf16 v[120:123], v[170:173], v[194:197], v[120:123]
	v_mfma_f32_16x16x32_bf16 v[108:111], v[162:165], v[202:205], v[108:111]
	v_mfma_f32_16x16x32_bf16 v[104:107], v[170:173], v[202:205], v[104:107]
	v_mfma_f32_16x16x32_bf16 v[92:95], v[162:165], v[210:213], v[92:95]
	v_mfma_f32_16x16x32_bf16 v[88:91], v[170:173], v[210:213], v[88:91]
	v_mfma_f32_16x16x32_bf16 v[76:79], v[162:165], v[218:221], v[76:79]
	v_mfma_f32_16x16x32_bf16 v[72:75], v[170:173], v[218:221], v[72:75]
	v_mfma_f32_16x16x32_bf16 v[116:119], v[174:177], v[190:193], v[116:119]
	v_mfma_f32_16x16x32_bf16 v[112:115], v[182:185], v[190:193], v[112:115]
	v_mfma_f32_16x16x32_bf16 v[100:103], v[174:177], v[198:201], v[100:103]
	v_mfma_f32_16x16x32_bf16 v[96:99], v[182:185], v[198:201], v[96:99]
	v_mfma_f32_16x16x32_bf16 v[84:87], v[174:177], v[206:209], v[84:87]
	v_mfma_f32_16x16x32_bf16 v[80:83], v[182:185], v[206:209], v[80:83]
	v_mfma_f32_16x16x32_bf16 v[68:71], v[174:177], v[214:217], v[68:71]
	v_mfma_f32_16x16x32_bf16 v[64:67], v[182:185], v[214:217], v[64:67]
	v_mfma_f32_16x16x32_bf16 v[116:119], v[178:181], v[194:197], v[116:119]
	v_mfma_f32_16x16x32_bf16 v[112:115], v[186:189], v[194:197], v[112:115]
	v_mfma_f32_16x16x32_bf16 v[100:103], v[178:181], v[202:205], v[100:103]
	v_mfma_f32_16x16x32_bf16 v[96:99], v[186:189], v[202:205], v[96:99]
	v_mfma_f32_16x16x32_bf16 v[84:87], v[178:181], v[210:213], v[84:87]
	v_mfma_f32_16x16x32_bf16 v[80:83], v[186:189], v[210:213], v[80:83]
	v_mfma_f32_16x16x32_bf16 v[68:71], v[178:181], v[218:221], v[68:71]
	v_mfma_f32_16x16x32_bf16 v[64:67], v[186:189], v[218:221], v[64:67]
	s_barrier
	s_add_i32 s57, s23, s11
	v_lshl_add_u64 v[144:145], s[46:47], 0, v[130:131]
	s_mov_b32 m0, s57
	ds_read_b128 v[190:193], v157 offset:16384
	ds_read_b128 v[194:197], v157 offset:17408
	ds_read_b128 v[198:201], v157 offset:18432
	ds_read_b128 v[202:205], v157 offset:19456
	ds_read_b128 v[206:209], v157 offset:20480
	ds_read_b128 v[210:213], v157 offset:21504
	ds_read_b128 v[214:217], v157 offset:22528
	ds_read_b128 v[218:221], v157 offset:23552
	global_load_lds_dwordx4 v[144:145], off
	s_add_i32 m0, s57, 0x2000
	s_add_u32 s58, s46, 0x80000
	v_lshl_add_u64 v[222:223], s[46:47], 0, v[134:135]
	s_addc_u32 s59, s47, 0
	s_add_i32 s57, s33, s11
	global_load_lds_dwordx4 v[222:223], off
	v_lshl_add_u64 v[224:225], s[58:59], 0, v[130:131]
	s_mov_b32 m0, s57
	v_lshl_add_u64 v[226:227], s[48:49], 0, v[132:133]
	global_load_lds_dwordx4 v[224:225], off
	v_lshl_add_u64 v[224:225], s[58:59], 0, v[134:135]
	s_add_i32 m0, s57, 0x2000
	s_nop 0
	global_load_lds_dwordx4 v[224:225], off
	v_lshl_add_u64 v[224:225], s[48:49], 0, v[128:129]
	s_mov_b32 m0, s14
	s_nop 0
	global_load_lds_dwordx4 v[224:225], off
	s_mov_b32 m0, s15
	s_nop 0
	global_load_lds_dwordx4 v[226:227], off
	s_waitcnt vmcnt(8)
	s_waitcnt lgkmcnt(0)
	s_barrier
; #define PG8_STAGE(bufoff, gbase, voff) do { _Pragma("unroll") for (int _i = 0; _i < 2; ++_i) \
;         __builtin_amdgcn_global_load_lds((const unsigned*)((const char*)(gbase) + (voff)[_i]), (LAS unsigned*)(lds + (bufoff) + ldsw + _i * 8192), 16, 0, 0); } while (0)
; #define PG8_LDA(dst, b, h) do { _Pragma("unroll") for (int m = 0; m < 4; ++m) _Pragma("unroll") for (int k = 0; k < 2; ++k) dst[m][k] = *(const LAS bf16x8*)(lds + PG8_SA(b, h) + aoff + m * 2048 + k * 1024); } while (0)
; #define PG8_LDB(dst, b, h) do { _Pragma("unroll") for (int n = 0; n < 2; ++n) _Pragma("unroll") for (int k = 0; k < 2; ++k) dst[n][k] = *(const LAS bf16x8*)(lds + PG8_SB(b, h) + boff + n * 2048 + k * 1024); } while (0)
; #define PG8_MMA(ai, bj, At, Bt) do { __builtin_amdgcn_s_setprio(1); _Pragma("unroll") for (int m = 0; m < 4; ++m) _Pragma("unroll") for (int n = 0; n < 2; ++n) _Pragma("unroll") for (int k = 0; k < 2; ++k) \
;         acc[ai][bj][m][n] = __builtin_amdgcn_mfma_f32_16x16x32_bf16(Bt[n][k], At[m][k], acc[ai][bj][m][n], 0, 0, 0); __builtin_amdgcn_s_setprio(0); } while (0)
; #define PG8_WAIT_V(n) asm volatile("s_waitcnt vmcnt(" #n ")" ::: "memory")
; #define PG8_WAIT_L(n) asm volatile("s_waitcnt lgkmcnt(" #n ")" ::: "memory")
; #define PG8_BAR __builtin_amdgcn_s_barrier()
; #define PG8_SCHED __builtin_amdgcn_sched_barrier(0)
; __device__ __forceinline__ void gemm_phase(LAS unsigned char* lds, const Params& p, const bf16_t* gA, const bf16_t* gBt, const int gM, const int gN, const int gK, const int epi, const int perm, bf16_t* const Hp, const int goff, const float coef) {
;     ...
;             PG8_WAIT_V(8); PG8_WAIT_L(0); PG8_BAR; PG8_MMA(1, 0, At, B0); PG8_MMA(1, 1, At, B1); PG8_BAR; PG8_SCHED;
;             PG8_LDB(B0, 1, 0); PG8_LDB(B1, 1, 1); PG8_SCHED; PG8_LDA(At, 1, 0); PG8_STAGE(PG8_SA(0, 1), a2 + hstep, voffA);
;             PG8_WAIT_V(8); PG8_WAIT_L(0); PG8_BAR; PG8_MMA(0, 0, At, B0); PG8_MMA(0, 1, At, B1); PG8_BAR; PG8_SCHED;
	s_waitcnt lgkmcnt(0)
	v_mfma_f32_16x16x32_bf16 v[60:63], v[158:161], v[190:193], v[60:63]
	v_mfma_f32_16x16x32_bf16 v[56:59], v[166:169], v[190:193], v[56:59]
	v_mfma_f32_16x16x32_bf16 v[44:47], v[158:161], v[198:201], v[44:47]
	v_mfma_f32_16x16x32_bf16 v[40:43], v[166:169], v[198:201], v[40:43]
	v_mfma_f32_16x16x32_bf16 v[28:31], v[158:161], v[206:209], v[28:31]
	v_mfma_f32_16x16x32_bf16 v[24:27], v[166:169], v[206:209], v[24:27]
	v_mfma_f32_16x16x32_bf16 v[12:15], v[158:161], v[214:217], v[12:15]
	v_mfma_f32_16x16x32_bf16 v[8:11], v[166:169], v[214:217], v[8:11]
	v_mfma_f32_16x16x32_bf16 v[60:63], v[162:165], v[194:197], v[60:63]
	v_mfma_f32_16x16x32_bf16 v[56:59], v[170:173], v[194:197], v[56:59]
	v_mfma_f32_16x16x32_bf16 v[44:47], v[162:165], v[202:205], v[44:47]
	v_mfma_f32_16x16x32_bf16 v[40:43], v[170:173], v[202:205], v[40:43]
	v_mfma_f32_16x16x32_bf16 v[28:31], v[162:165], v[210:213], v[28:31]
	v_mfma_f32_16x16x32_bf16 v[24:27], v[170:173], v[210:213], v[24:27]
	v_mfma_f32_16x16x32_bf16 v[12:15], v[162:165], v[218:221], v[12:15]
	v_mfma_f32_16x16x32_bf16 v[8:11], v[170:173], v[218:221], v[8:11]
	v_mfma_f32_16x16x32_bf16 v[52:55], v[174:177], v[190:193], v[52:55]
	v_mfma_f32_16x16x32_bf16 v[48:51], v[182:185], v[190:193], v[48:51]
	v_mfma_f32_16x16x32_bf16 v[36:39], v[174:177], v[198:201], v[36:39]
	v_mfma_f32_16x16x32_bf16 v[32:35], v[182:185], v[198:201], v[32:35]
	v_mfma_f32_16x16x32_bf16 v[20:23], v[174:177], v[206:209], v[20:23]
	v_mfma_f32_16x16x32_bf16 v[16:19], v[182:185], v[206:209], v[16:19]
	v_mfma_f32_16x16x32_bf16 v[4:7], v[174:177], v[214:217], v[4:7]
	v_mfma_f32_16x16x32_bf16 v[0:3], v[182:185], v[214:217], v[0:3]
	v_mfma_f32_16x16x32_bf16 v[52:55], v[178:181], v[194:197], v[52:55]
	v_mfma_f32_16x16x32_bf16 v[48:51], v[186:189], v[194:197], v[48:51]
	v_mfma_f32_16x16x32_bf16 v[36:39], v[178:181], v[202:205], v[36:39]
	v_mfma_f32_16x16x32_bf16 v[32:35], v[186:189], v[202:205], v[32:35]
	v_mfma_f32_16x16x32_bf16 v[20:23], v[178:181], v[210:213], v[20:23]
	v_mfma_f32_16x16x32_bf16 v[16:19], v[186:189], v[210:213], v[16:19]
	v_mfma_f32_16x16x32_bf16 v[4:7], v[178:181], v[218:221], v[4:7]
	v_mfma_f32_16x16x32_bf16 v[0:3], v[186:189], v[218:221], v[0:3]
	s_barrier
	s_add_i32 s57, 0, 0x18000
	s_add_i32 s58, 0, 0x1c000
	v_add_u32_e32 v170, s57, v146
	v_add_u32_e32 v186, s58, v146
	ds_read_b128 v[158:161], v170
	ds_read_b128 v[162:165], v170 offset:1024
	ds_read_b128 v[166:169], v170 offset:2048
	ds_read_b128 v[170:173], v170 offset:3072
	ds_read_b128 v[174:177], v186
	ds_read_b128 v[178:181], v186 offset:1024
	ds_read_b128 v[182:185], v186 offset:2048
	ds_read_b128 v[186:189], v186 offset:3072
	s_add_u32 s48, s48, 0x80000
	s_addc_u32 s49, s49, 0
	s_mov_b32 m0, s16
	v_lshl_add_u64 v[228:229], s[48:49], 0, v[128:129]
	ds_read_b128 v[190:193], v157 offset:32768
	ds_read_b128 v[194:197], v157 offset:33792
	ds_read_b128 v[198:201], v157 offset:34816
	ds_read_b128 v[202:205], v157 offset:35840
	ds_read_b128 v[206:209], v157 offset:36864
	ds_read_b128 v[210:213], v157 offset:37888
	ds_read_b128 v[214:217], v157 offset:38912
	ds_read_b128 v[218:221], v157 offset:39936
	global_load_lds_dwordx4 v[228:229], off
	v_lshl_add_u64 v[228:229], s[48:49], 0, v[132:133]
	s_mov_b32 m0, s17
	s_nop 0
	global_load_lds_dwordx4 v[228:229], off
	s_waitcnt vmcnt(8)
	s_waitcnt lgkmcnt(0)
	s_barrier
	s_waitcnt lgkmcnt(0)
	v_mfma_f32_16x16x32_bf16 v[124:127], v[158:161], v[190:193], v[124:127]
	v_mfma_f32_16x16x32_bf16 v[120:123], v[166:169], v[190:193], v[120:123]
	v_mfma_f32_16x16x32_bf16 v[108:111], v[158:161], v[198:201], v[108:111]
	v_mfma_f32_16x16x32_bf16 v[104:107], v[166:169], v[198:201], v[104:107]
	v_mfma_f32_16x16x32_bf16 v[92:95], v[158:161], v[206:209], v[92:95]
	v_mfma_f32_16x16x32_bf16 v[88:91], v[166:169], v[206:209], v[88:91]
	v_mfma_f32_16x16x32_bf16 v[76:79], v[158:161], v[214:217], v[76:79]
	v_mfma_f32_16x16x32_bf16 v[72:75], v[166:169], v[214:217], v[72:75]
	v_mfma_f32_16x16x32_bf16 v[124:127], v[162:165], v[194:197], v[124:127]
	v_mfma_f32_16x16x32_bf16 v[120:123], v[170:173], v[194:197], v[120:123]
	v_mfma_f32_16x16x32_bf16 v[108:111], v[162:165], v[202:205], v[108:111]
	v_mfma_f32_16x16x32_bf16 v[104:107], v[170:173], v[202:205], v[104:107]
	v_mfma_f32_16x16x32_bf16 v[92:95], v[162:165], v[210:213], v[92:95]
	v_mfma_f32_16x16x32_bf16 v[88:91], v[170:173], v[210:213], v[88:91]
	v_mfma_f32_16x16x32_bf16 v[76:79], v[162:165], v[218:221], v[76:79]
	v_mfma_f32_16x16x32_bf16 v[72:75], v[170:173], v[218:221], v[72:75]
	v_mfma_f32_16x16x32_bf16 v[116:119], v[174:177], v[190:193], v[116:119]
	v_mfma_f32_16x16x32_bf16 v[112:115], v[182:185], v[190:193], v[112:115]
	v_mfma_f32_16x16x32_bf16 v[100:103], v[174:177], v[198:201], v[100:103]
	v_mfma_f32_16x16x32_bf16 v[96:99], v[182:185], v[198:201], v[96:99]
	v_mfma_f32_16x16x32_bf16 v[84:87], v[174:177], v[206:209], v[84:87]
	v_mfma_f32_16x16x32_bf16 v[80:83], v[182:185], v[206:209], v[80:83]
	v_mfma_f32_16x16x32_bf16 v[68:71], v[174:177], v[214:217], v[68:71]
	v_mfma_f32_16x16x32_bf16 v[64:67], v[182:185], v[214:217], v[64:67]
	v_mfma_f32_16x16x32_bf16 v[116:119], v[178:181], v[194:197], v[116:119]
	v_mfma_f32_16x16x32_bf16 v[112:115], v[186:189], v[194:197], v[112:115]
	v_mfma_f32_16x16x32_bf16 v[100:103], v[178:181], v[202:205], v[100:103]
	v_mfma_f32_16x16x32_bf16 v[96:99], v[186:189], v[202:205], v[96:99]
	v_mfma_f32_16x16x32_bf16 v[84:87], v[178:181], v[210:213], v[84:87]
	v_mfma_f32_16x16x32_bf16 v[80:83], v[186:189], v[210:213], v[80:83]
	v_mfma_f32_16x16x32_bf16 v[68:71], v[178:181], v[218:221], v[68:71]
	v_mfma_f32_16x16x32_bf16 v[64:67], v[186:189], v[218:221], v[64:67]
	s_barrier
; #define PG8_STAGE(bufoff, gbase, voff) do { _Pragma("unroll") for (int _i = 0; _i < 2; ++_i) \
;         __builtin_amdgcn_global_load_lds((const unsigned*)((const char*)(gbase) + (voff)[_i]), (LAS unsigned*)(lds + (bufoff) + ldsw + _i * 8192), 16, 0, 0); } while (0)
; #define PG8_LDA(dst, b, h) do { _Pragma("unroll") for (int m = 0; m < 4; ++m) _Pragma("unroll") for (int k = 0; k < 2; ++k) dst[m][k] = *(const LAS bf16x8*)(lds + PG8_SA(b, h) + aoff + m * 2048 + k * 1024); } while (0)
; #define PG8_MMA(ai, bj, At, Bt) do { __builtin_amdgcn_s_setprio(1); _Pragma("unroll") for (int m = 0; m < 4; ++m) _Pragma("unroll") for (int n = 0; n < 2; ++n) _Pragma("unroll") for (int k = 0; k < 2; ++k) \
;         acc[ai][bj][m][n] = __builtin_amdgcn_mfma_f32_16x16x32_bf16(Bt[n][k], At[m][k], acc[ai][bj][m][n], 0, 0, 0); __builtin_amdgcn_s_setprio(0); } while (0)
; #define PG8_WAIT_V(n) asm volatile("s_waitcnt vmcnt(" #n ")" ::: "memory")
; #define PG8_WAIT_L(n) asm volatile("s_waitcnt lgkmcnt(" #n ")" ::: "memory")
; #define PG8_BAR __builtin_amdgcn_s_barrier()
; #define PG8_SCHED __builtin_amdgcn_sched_barrier(0)
; __device__ __forceinline__ void gemm_phase(LAS unsigned char* lds, const Params& p, const bf16_t* gA, const bf16_t* gBt, const int gM, const int gN, const int gK, const int epi, const int perm, bf16_t* const Hp, const int goff, const float coef) {
;     ...
;             PG8_LDA(At, 1, 1); PG8_STAGE(PG8_SB(1, 0), b3, voffB); PG8_STAGE(PG8_SB(1, 1), b3 + hstep, voffB); PG8_STAGE(PG8_SA(1, 0), a3, voffA);
;             PG8_WAIT_V(8); PG8_WAIT_L(0); PG8_BAR; PG8_MMA(1, 0, At, B0); PG8_MMA(1, 1, At, B1); PG8_BAR; PG8_SCHED;
;         }
;         if (wr == 0) PG8_BAR;
	s_add_i32 s48, s57, s11
	v_lshl_add_u64 v[144:145], v[144:145], 0, s[8:9]
	s_mov_b32 m0, s48
	ds_read_b128 v[190:193], v157 offset:49152
	ds_read_b128 v[194:197], v157 offset:50176
	ds_read_b128 v[198:201], v157 offset:51200
	ds_read_b128 v[202:205], v157 offset:52224
	ds_read_b128 v[206:209], v157 offset:53248
	ds_read_b128 v[210:213], v157 offset:54272
	ds_read_b128 v[214:217], v157 offset:55296
	ds_read_b128 v[218:221], v157 offset:56320
	global_load_lds_dwordx4 v[144:145], off
	s_add_i32 m0, s48, 0x2000
	s_add_u32 s46, s46, 0x80080
	v_lshl_add_u64 v[144:145], v[222:223], 0, s[8:9]
	s_addc_u32 s47, s47, 0
	s_add_i32 s48, s58, s11
	global_load_lds_dwordx4 v[144:145], off
	v_lshl_add_u64 v[144:145], s[46:47], 0, v[130:131]
	s_mov_b32 m0, s48
	s_nop 0
	global_load_lds_dwordx4 v[144:145], off
	v_lshl_add_u64 v[144:145], s[46:47], 0, v[134:135]
	s_add_i32 m0, s48, 0x2000
	s_nop 0
	global_load_lds_dwordx4 v[144:145], off
	v_lshl_add_u64 v[144:145], v[224:225], 0, s[8:9]
	s_mov_b32 m0, s19
	s_nop 0
	global_load_lds_dwordx4 v[144:145], off
	v_lshl_add_u64 v[144:145], v[226:227], 0, s[8:9]
	s_mov_b32 m0, s20
	s_nop 0
	global_load_lds_dwordx4 v[144:145], off
	s_waitcnt vmcnt(8)
	s_waitcnt lgkmcnt(0)
	s_barrier
	s_waitcnt lgkmcnt(0)
	v_mfma_f32_16x16x32_bf16 v[60:63], v[158:161], v[190:193], v[60:63]
	v_mfma_f32_16x16x32_bf16 v[56:59], v[166:169], v[190:193], v[56:59]
	v_mfma_f32_16x16x32_bf16 v[44:47], v[158:161], v[198:201], v[44:47]
	v_mfma_f32_16x16x32_bf16 v[40:43], v[166:169], v[198:201], v[40:43]
	v_mfma_f32_16x16x32_bf16 v[28:31], v[158:161], v[206:209], v[28:31]
	v_mfma_f32_16x16x32_bf16 v[24:27], v[166:169], v[206:209], v[24:27]
	v_mfma_f32_16x16x32_bf16 v[12:15], v[158:161], v[214:217], v[12:15]
	v_mfma_f32_16x16x32_bf16 v[8:11], v[166:169], v[214:217], v[8:11]
	v_mfma_f32_16x16x32_bf16 v[60:63], v[162:165], v[194:197], v[60:63]
	v_mfma_f32_16x16x32_bf16 v[56:59], v[170:173], v[194:197], v[56:59]
	v_mfma_f32_16x16x32_bf16 v[44:47], v[162:165], v[202:205], v[44:47]
	v_mfma_f32_16x16x32_bf16 v[40:43], v[170:173], v[202:205], v[40:43]
	v_mfma_f32_16x16x32_bf16 v[28:31], v[162:165], v[210:213], v[28:31]
	v_mfma_f32_16x16x32_bf16 v[24:27], v[170:173], v[210:213], v[24:27]
	v_mfma_f32_16x16x32_bf16 v[12:15], v[162:165], v[218:221], v[12:15]
	v_mfma_f32_16x16x32_bf16 v[8:11], v[170:173], v[218:221], v[8:11]
	v_mfma_f32_16x16x32_bf16 v[52:55], v[174:177], v[190:193], v[52:55]
	v_mfma_f32_16x16x32_bf16 v[48:51], v[182:185], v[190:193], v[48:51]
	v_mfma_f32_16x16x32_bf16 v[36:39], v[174:177], v[198:201], v[36:39]
	v_mfma_f32_16x16x32_bf16 v[32:35], v[182:185], v[198:201], v[32:35]
	v_mfma_f32_16x16x32_bf16 v[20:23], v[174:177], v[206:209], v[20:23]
	v_mfma_f32_16x16x32_bf16 v[16:19], v[182:185], v[206:209], v[16:19]
	v_mfma_f32_16x16x32_bf16 v[4:7], v[174:177], v[214:217], v[4:7]
	v_mfma_f32_16x16x32_bf16 v[0:3], v[182:185], v[214:217], v[0:3]
	v_mfma_f32_16x16x32_bf16 v[52:55], v[178:181], v[194:197], v[52:55]
	v_mfma_f32_16x16x32_bf16 v[48:51], v[186:189], v[194:197], v[48:51]
	v_mfma_f32_16x16x32_bf16 v[36:39], v[178:181], v[202:205], v[36:39]
	v_mfma_f32_16x16x32_bf16 v[32:35], v[186:189], v[202:205], v[32:35]
	v_mfma_f32_16x16x32_bf16 v[20:23], v[178:181], v[210:213], v[20:23]
	v_mfma_f32_16x16x32_bf16 v[16:19], v[186:189], v[210:213], v[16:19]
	v_mfma_f32_16x16x32_bf16 v[4:7], v[178:181], v[218:221], v[4:7]
	v_mfma_f32_16x16x32_bf16 v[0:3], v[186:189], v[218:221], v[0:3]
	s_barrier
	s_add_u32 s44, s44, 0x100
	s_addc_u32 s45, s45, 0
	s_add_u32 s54, s54, 0x100
	s_addc_u32 s55, s55, 0
	s_cmp_ge_u32 s56, s52
	s_mov_b32 s48, s56
	s_cbranch_scc0 .LBB0_170
	s_and_b64 vcc, exec, s[12:13]
	s_cbranch_vccz .LBB0_173
	s_barrier

; #define PG8_STAGE(bufoff, gbase, voff) do { _Pragma("unroll") for (int _i = 0; _i < 2; ++_i) \
;         __builtin_amdgcn_global_load_lds((const unsigned*)((const char*)(gbase) + (voff)[_i]), (LAS unsigned*)(lds + (bufoff) + ldsw + _i * 8192), 16, 0, 0); } while (0)
; #define PG8_LDA(dst, b, h) do { _Pragma("unroll") for (int m = 0; m < 4; ++m) _Pragma("unroll") for (int k = 0; k < 2; ++k) dst[m][k] = *(const LAS bf16x8*)(lds + PG8_SA(b, h) + aoff + m * 2048 + k * 1024); } while (0)
; #define PG8_LDB(dst, b, h) do { _Pragma("unroll") for (int n = 0; n < 2; ++n) _Pragma("unroll") for (int k = 0; k < 2; ++k) dst[n][k] = *(const LAS bf16x8*)(lds + PG8_SB(b, h) + boff + n * 2048 + k * 1024); } while (0)
; #define PG8_MMA(ai, bj, At, Bt) do { __builtin_amdgcn_s_setprio(1); _Pragma("unroll") for (int m = 0; m < 4; ++m) _Pragma("unroll") for (int n = 0; n < 2; ++n) _Pragma("unroll") for (int k = 0; k < 2; ++k) \
;         acc[ai][bj][m][n] = __builtin_amdgcn_mfma_f32_16x16x32_bf16(Bt[n][k], At[m][k], acc[ai][bj][m][n], 0, 0, 0); __builtin_amdgcn_s_setprio(0); } while (0)
; #define PG8_WAIT_V(n) asm volatile("s_waitcnt vmcnt(" #n ")" ::: "memory")
; #define PG8_WAIT_L(n) asm volatile("s_waitcnt lgkmcnt(" #n ")" ::: "memory")
; #define PG8_BAR __builtin_amdgcn_s_barrier()
; #define PG8_SCHED __builtin_amdgcn_sched_barrier(0)
; __device__ __forceinline__ void gemm_phase(LAS unsigned char* lds, const Params& p, const bf16_t* gA, const bf16_t* gBt, const int gM, const int gN, const int gK, const int epi, const int perm, bf16_t* const Hp, const int goff, const float coef) {
;     ...
;         for (int t = 0; t < nt; t += 2) {
;             const bool last = (t == nt - 2);
;             const char* a1 = cA + (size_t)(t + 1) * kstep;
;             const char* a2 = last ? nA : cA + (size_t)(t + 2) * kstep; const char* b2 = last ? nB : cB + (size_t)(t + 2) * kstep;
;             const char* a3 = a2 + kstep; const char* b3 = b2 + kstep;
;             PG8_LDB(B0, 0, 0); PG8_LDB(B1, 0, 1); PG8_SCHED; PG8_LDA(At, 0, 0); PG8_STAGE(PG8_SA(1, 1), a1 + hstep, voffA);
;             PG8_WAIT_V(8); PG8_WAIT_L(0); PG8_BAR; PG8_MMA(0, 0, At, B0); PG8_MMA(0, 1, At, B1); PG8_BAR; PG8_SCHED;
;             PG8_LDA(At, 0, 1); PG8_STAGE(PG8_SB(0, 0), b2, voffB); PG8_STAGE(PG8_SB(0, 1), b2 + hstep, voffB); PG8_STAGE(PG8_SA(0, 0), a2, voffA);
.LBB0_264:
	ds_read_b128 v[146:149], v167
	ds_read_b128 v[150:153], v167 offset:1024
	ds_read_b128 v[154:157], v167 offset:2048
	ds_read_b128 v[170:173], v167 offset:3072
	ds_read_b128 v[174:177], v168
	ds_read_b128 v[178:181], v168 offset:1024
	ds_read_b128 v[182:185], v168 offset:2048
	ds_read_b128 v[186:189], v168 offset:3072
	s_add_i32 s58, s34, 2
	s_add_u32 s35, s30, 0xffea0080
	s_addc_u32 s38, s31, -1
	s_cmp_eq_u32 s55, s34
	s_cselect_b32 s34, s28, s56
	s_cselect_b32 s39, s27, s38
	s_cselect_b32 s38, s26, s35
	s_cselect_b32 s35, s29, s57
	v_lshl_add_u64 v[222:223], s[30:31], 0, v[136:137]
	s_add_i32 m0, s17, 0xc000
	ds_read_b128 v[190:193], v169
	ds_read_b128 v[194:197], v169 offset:1024
	ds_read_b128 v[198:201], v169 offset:2048
	ds_read_b128 v[202:205], v169 offset:3072
	ds_read_b128 v[206:209], v169 offset:4096
	ds_read_b128 v[210:213], v169 offset:5120
	ds_read_b128 v[214:217], v169 offset:6144
	ds_read_b128 v[218:221], v169 offset:7168
	global_load_lds_dwordx4 v[222:223], off
	v_lshl_add_u64 v[222:223], s[30:31], 0, v[138:139]
	s_add_i32 m0, s17, 0xe000
	s_nop 0
	global_load_lds_dwordx4 v[222:223], off
	s_waitcnt vmcnt(8)
	s_waitcnt lgkmcnt(0)
	s_barrier
	s_waitcnt lgkmcnt(0)
	v_mfma_f32_16x16x32_bf16 v[124:127], v[146:149], v[190:193], v[124:127]
	v_mfma_f32_16x16x32_bf16 v[120:123], v[154:157], v[190:193], v[120:123]
	v_mfma_f32_16x16x32_bf16 v[116:119], v[146:149], v[198:201], v[116:119]
	v_mfma_f32_16x16x32_bf16 v[112:115], v[154:157], v[198:201], v[112:115]
	v_mfma_f32_16x16x32_bf16 v[108:111], v[146:149], v[206:209], v[108:111]
	v_mfma_f32_16x16x32_bf16 v[104:107], v[154:157], v[206:209], v[104:107]
	v_mfma_f32_16x16x32_bf16 v[100:103], v[146:149], v[214:217], v[100:103]
	v_mfma_f32_16x16x32_bf16 v[96:99], v[154:157], v[214:217], v[96:99]
	v_mfma_f32_16x16x32_bf16 v[124:127], v[150:153], v[194:197], v[124:127]
	v_mfma_f32_16x16x32_bf16 v[120:123], v[170:173], v[194:197], v[120:123]
	v_mfma_f32_16x16x32_bf16 v[116:119], v[150:153], v[202:205], v[116:119]
	v_mfma_f32_16x16x32_bf16 v[112:115], v[170:173], v[202:205], v[112:115]
	v_mfma_f32_16x16x32_bf16 v[108:111], v[150:153], v[210:213], v[108:111]
	v_mfma_f32_16x16x32_bf16 v[104:107], v[170:173], v[210:213], v[104:107]
	v_mfma_f32_16x16x32_bf16 v[100:103], v[150:153], v[218:221], v[100:103]
	v_mfma_f32_16x16x32_bf16 v[96:99], v[170:173], v[218:221], v[96:99]
	v_mfma_f32_16x16x32_bf16 v[68:71], v[174:177], v[190:193], v[68:71]
	v_mfma_f32_16x16x32_bf16 v[60:63], v[182:185], v[190:193], v[60:63]
	v_mfma_f32_16x16x32_bf16 v[52:55], v[174:177], v[198:201], v[52:55]
	v_mfma_f32_16x16x32_bf16 v[48:51], v[182:185], v[198:201], v[48:51]
	v_mfma_f32_16x16x32_bf16 v[44:47], v[174:177], v[206:209], v[44:47]
	v_mfma_f32_16x16x32_bf16 v[40:43], v[182:185], v[206:209], v[40:43]
	v_mfma_f32_16x16x32_bf16 v[36:39], v[174:177], v[214:217], v[36:39]
	v_mfma_f32_16x16x32_bf16 v[32:35], v[182:185], v[214:217], v[32:35]
	v_mfma_f32_16x16x32_bf16 v[68:71], v[178:181], v[194:197], v[68:71]
	v_mfma_f32_16x16x32_bf16 v[60:63], v[186:189], v[194:197], v[60:63]
	v_mfma_f32_16x16x32_bf16 v[52:55], v[178:181], v[202:205], v[52:55]
	v_mfma_f32_16x16x32_bf16 v[48:51], v[186:189], v[202:205], v[48:51]
	v_mfma_f32_16x16x32_bf16 v[44:47], v[178:181], v[210:213], v[44:47]
	v_mfma_f32_16x16x32_bf16 v[40:43], v[186:189], v[210:213], v[40:43]
	v_mfma_f32_16x16x32_bf16 v[36:39], v[178:181], v[218:221], v[36:39]
	v_mfma_f32_16x16x32_bf16 v[32:35], v[186:189], v[218:221], v[32:35]
	s_barrier
	s_add_i32 s59, s46, s16
	v_lshl_add_u64 v[222:223], s[34:35], 0, v[130:131]
	s_mov_b32 m0, s59
	ds_read_b128 v[190:193], v169 offset:16384
	ds_read_b128 v[194:197], v169 offset:17408
	ds_read_b128 v[198:201], v169 offset:18432
	ds_read_b128 v[202:205], v169 offset:19456
	ds_read_b128 v[206:209], v169 offset:20480
	ds_read_b128 v[210:213], v169 offset:21504
	ds_read_b128 v[214:217], v169 offset:22528
	ds_read_b128 v[218:221], v169 offset:23552
	global_load_lds_dwordx4 v[222:223], off
	s_add_i32 m0, s59, 0x2000
	s_add_u32 s60, s34, 0x160000
	v_lshl_add_u64 v[224:225], s[34:35], 0, v[134:135]
	s_addc_u32 s61, s35, 0
	s_add_i32 s59, s47, s16
	global_load_lds_dwordx4 v[224:225], off
	v_lshl_add_u64 v[226:227], s[60:61], 0, v[130:131]
	s_mov_b32 m0, s59
	v_lshl_add_u64 v[228:229], s[38:39], 0, v[132:133]
	global_load_lds_dwordx4 v[226:227], off
	v_lshl_add_u64 v[226:227], s[60:61], 0, v[134:135]
	s_add_i32 m0, s59, 0x2000
	s_nop 0
	global_load_lds_dwordx4 v[226:227], off
	v_lshl_add_u64 v[226:227], s[38:39], 0, v[128:129]
	s_mov_b32 m0, s17
	s_nop 0
	global_load_lds_dwordx4 v[226:227], off
	s_mov_b32 m0, s18
	s_nop 0
	global_load_lds_dwordx4 v[228:229], off
	s_waitcnt vmcnt(8)
	s_waitcnt lgkmcnt(0)
	s_barrier
; #define PG8_STAGE(bufoff, gbase, voff) do { _Pragma("unroll") for (int _i = 0; _i < 2; ++_i) \
;         __builtin_amdgcn_global_load_lds((const unsigned*)((const char*)(gbase) + (voff)[_i]), (LAS unsigned*)(lds + (bufoff) + ldsw + _i * 8192), 16, 0, 0); } while (0)
; #define PG8_LDA(dst, b, h) do { _Pragma("unroll") for (int m = 0; m < 4; ++m) _Pragma("unroll") for (int k = 0; k < 2; ++k) dst[m][k] = *(const LAS bf16x8*)(lds + PG8_SA(b, h) + aoff + m * 2048 + k * 1024); } while (0)
; #define PG8_LDB(dst, b, h) do { _Pragma("unroll") for (int n = 0; n < 2; ++n) _Pragma("unroll") for (int k = 0; k < 2; ++k) dst[n][k] = *(const LAS bf16x8*)(lds + PG8_SB(b, h) + boff + n * 2048 + k * 1024); } while (0)
; #define PG8_MMA(ai, bj, At, Bt) do { __builtin_amdgcn_s_setprio(1); _Pragma("unroll") for (int m = 0; m < 4; ++m) _Pragma("unroll") for (int n = 0; n < 2; ++n) _Pragma("unroll") for (int k = 0; k < 2; ++k) \
;         acc[ai][bj][m][n] = __builtin_amdgcn_mfma_f32_16x16x32_bf16(Bt[n][k], At[m][k], acc[ai][bj][m][n], 0, 0, 0); __builtin_amdgcn_s_setprio(0); } while (0)
; #define PG8_WAIT_V(n) asm volatile("s_waitcnt vmcnt(" #n ")" ::: "memory")
; #define PG8_WAIT_L(n) asm volatile("s_waitcnt lgkmcnt(" #n ")" ::: "memory")
; #define PG8_BAR __builtin_amdgcn_s_barrier()
; #define PG8_SCHED __builtin_amdgcn_sched_barrier(0)
; __device__ __forceinline__ void gemm_phase(LAS unsigned char* lds, const Params& p, const bf16_t* gA, const bf16_t* gBt, const int gM, const int gN, const int gK, const int epi, const int perm, bf16_t* const Hp, const int goff, const float coef) {
;     ...
;             PG8_WAIT_V(8); PG8_WAIT_L(0); PG8_BAR; PG8_MMA(1, 0, At, B0); PG8_MMA(1, 1, At, B1); PG8_BAR; PG8_SCHED;
;             PG8_LDB(B0, 1, 0); PG8_LDB(B1, 1, 1); PG8_SCHED; PG8_LDA(At, 1, 0); PG8_STAGE(PG8_SA(0, 1), a2 + hstep, voffA);
;             PG8_WAIT_V(8); PG8_WAIT_L(0); PG8_BAR; PG8_MMA(0, 0, At, B0); PG8_MMA(0, 1, At, B1); PG8_BAR; PG8_SCHED;
	s_waitcnt lgkmcnt(0)
	v_mfma_f32_16x16x32_bf16 v[92:95], v[146:149], v[190:193], v[92:95]
	v_mfma_f32_16x16x32_bf16 v[88:91], v[154:157], v[190:193], v[88:91]
	v_mfma_f32_16x16x32_bf16 v[84:87], v[146:149], v[198:201], v[84:87]
	v_mfma_f32_16x16x32_bf16 v[80:83], v[154:157], v[198:201], v[80:83]
	v_mfma_f32_16x16x32_bf16 v[76:79], v[146:149], v[206:209], v[76:79]
	v_mfma_f32_16x16x32_bf16 v[72:75], v[154:157], v[206:209], v[72:75]
	v_mfma_f32_16x16x32_bf16 v[64:67], v[146:149], v[214:217], v[64:67]
	v_mfma_f32_16x16x32_bf16 v[56:59], v[154:157], v[214:217], v[56:59]
	v_mfma_f32_16x16x32_bf16 v[92:95], v[150:153], v[194:197], v[92:95]
	v_mfma_f32_16x16x32_bf16 v[88:91], v[170:173], v[194:197], v[88:91]
	v_mfma_f32_16x16x32_bf16 v[84:87], v[150:153], v[202:205], v[84:87]
	v_mfma_f32_16x16x32_bf16 v[80:83], v[170:173], v[202:205], v[80:83]
	v_mfma_f32_16x16x32_bf16 v[76:79], v[150:153], v[210:213], v[76:79]
	v_mfma_f32_16x16x32_bf16 v[72:75], v[170:173], v[210:213], v[72:75]
	v_mfma_f32_16x16x32_bf16 v[64:67], v[150:153], v[218:221], v[64:67]
	v_mfma_f32_16x16x32_bf16 v[56:59], v[170:173], v[218:221], v[56:59]
	v_mfma_f32_16x16x32_bf16 v[28:31], v[174:177], v[190:193], v[28:31]
	v_mfma_f32_16x16x32_bf16 v[24:27], v[182:185], v[190:193], v[24:27]
	v_mfma_f32_16x16x32_bf16 v[20:23], v[174:177], v[198:201], v[20:23]
	v_mfma_f32_16x16x32_bf16 v[16:19], v[182:185], v[198:201], v[16:19]
	v_mfma_f32_16x16x32_bf16 v[12:15], v[174:177], v[206:209], v[12:15]
	v_mfma_f32_16x16x32_bf16 v[8:11], v[182:185], v[206:209], v[8:11]
	v_mfma_f32_16x16x32_bf16 v[4:7], v[174:177], v[214:217], v[4:7]
	v_mfma_f32_16x16x32_bf16 v[0:3], v[182:185], v[214:217], v[0:3]
	v_mfma_f32_16x16x32_bf16 v[28:31], v[178:181], v[194:197], v[28:31]
	v_mfma_f32_16x16x32_bf16 v[24:27], v[186:189], v[194:197], v[24:27]
	v_mfma_f32_16x16x32_bf16 v[20:23], v[178:181], v[202:205], v[20:23]
	v_mfma_f32_16x16x32_bf16 v[16:19], v[186:189], v[202:205], v[16:19]
	v_mfma_f32_16x16x32_bf16 v[12:15], v[178:181], v[210:213], v[12:15]
	v_mfma_f32_16x16x32_bf16 v[8:11], v[186:189], v[210:213], v[8:11]
	v_mfma_f32_16x16x32_bf16 v[4:7], v[178:181], v[218:221], v[4:7]
	v_mfma_f32_16x16x32_bf16 v[0:3], v[186:189], v[218:221], v[0:3]
	s_barrier
	s_add_i32 s59, 0, 0x18000
	s_add_i32 s60, 0, 0x1c000
	v_add_u32_e32 v170, s59, v158
	v_add_u32_e32 v186, s60, v158
	ds_read_b128 v[146:149], v170
	ds_read_b128 v[150:153], v170 offset:1024
	ds_read_b128 v[154:157], v170 offset:2048
	ds_read_b128 v[170:173], v170 offset:3072
	ds_read_b128 v[174:177], v186
	ds_read_b128 v[178:181], v186 offset:1024
	ds_read_b128 v[182:185], v186 offset:2048
	ds_read_b128 v[186:189], v186 offset:3072
	s_add_u32 s38, s38, 0x160000
	s_addc_u32 s39, s39, 0
	s_mov_b32 m0, s19
	v_lshl_add_u64 v[230:231], s[38:39], 0, v[128:129]
	ds_read_b128 v[190:193], v169 offset:32768
	ds_read_b128 v[194:197], v169 offset:33792
	ds_read_b128 v[198:201], v169 offset:34816
	ds_read_b128 v[202:205], v169 offset:35840
	ds_read_b128 v[206:209], v169 offset:36864
	ds_read_b128 v[210:213], v169 offset:37888
	ds_read_b128 v[214:217], v169 offset:38912
	ds_read_b128 v[218:221], v169 offset:39936
	global_load_lds_dwordx4 v[230:231], off
	v_lshl_add_u64 v[230:231], s[38:39], 0, v[132:133]
	s_mov_b32 m0, s20
	s_nop 0
	global_load_lds_dwordx4 v[230:231], off
	s_waitcnt vmcnt(8)
	s_waitcnt lgkmcnt(0)
	s_barrier
	s_waitcnt lgkmcnt(0)
	v_mfma_f32_16x16x32_bf16 v[124:127], v[146:149], v[190:193], v[124:127]
	v_mfma_f32_16x16x32_bf16 v[120:123], v[154:157], v[190:193], v[120:123]
	v_mfma_f32_16x16x32_bf16 v[116:119], v[146:149], v[198:201], v[116:119]
	v_mfma_f32_16x16x32_bf16 v[112:115], v[154:157], v[198:201], v[112:115]
	v_mfma_f32_16x16x32_bf16 v[108:111], v[146:149], v[206:209], v[108:111]
	v_mfma_f32_16x16x32_bf16 v[104:107], v[154:157], v[206:209], v[104:107]
	v_mfma_f32_16x16x32_bf16 v[100:103], v[146:149], v[214:217], v[100:103]
	v_mfma_f32_16x16x32_bf16 v[96:99], v[154:157], v[214:217], v[96:99]
	v_mfma_f32_16x16x32_bf16 v[124:127], v[150:153], v[194:197], v[124:127]
	v_mfma_f32_16x16x32_bf16 v[120:123], v[170:173], v[194:197], v[120:123]
	v_mfma_f32_16x16x32_bf16 v[116:119], v[150:153], v[202:205], v[116:119]
	v_mfma_f32_16x16x32_bf16 v[112:115], v[170:173], v[202:205], v[112:115]
	v_mfma_f32_16x16x32_bf16 v[108:111], v[150:153], v[210:213], v[108:111]
	v_mfma_f32_16x16x32_bf16 v[104:107], v[170:173], v[210:213], v[104:107]
	v_mfma_f32_16x16x32_bf16 v[100:103], v[150:153], v[218:221], v[100:103]
	v_mfma_f32_16x16x32_bf16 v[96:99], v[170:173], v[218:221], v[96:99]
	v_mfma_f32_16x16x32_bf16 v[68:71], v[174:177], v[190:193], v[68:71]
	v_mfma_f32_16x16x32_bf16 v[60:63], v[182:185], v[190:193], v[60:63]
	v_mfma_f32_16x16x32_bf16 v[52:55], v[174:177], v[198:201], v[52:55]
	v_mfma_f32_16x16x32_bf16 v[48:51], v[182:185], v[198:201], v[48:51]
	v_mfma_f32_16x16x32_bf16 v[44:47], v[174:177], v[206:209], v[44:47]
	v_mfma_f32_16x16x32_bf16 v[40:43], v[182:185], v[206:209], v[40:43]
	v_mfma_f32_16x16x32_bf16 v[36:39], v[174:177], v[214:217], v[36:39]
	v_mfma_f32_16x16x32_bf16 v[32:35], v[182:185], v[214:217], v[32:35]
	v_mfma_f32_16x16x32_bf16 v[68:71], v[178:181], v[194:197], v[68:71]
	v_mfma_f32_16x16x32_bf16 v[60:63], v[186:189], v[194:197], v[60:63]
	v_mfma_f32_16x16x32_bf16 v[52:55], v[178:181], v[202:205], v[52:55]
	v_mfma_f32_16x16x32_bf16 v[48:51], v[186:189], v[202:205], v[48:51]
	v_mfma_f32_16x16x32_bf16 v[44:47], v[178:181], v[210:213], v[44:47]
	v_mfma_f32_16x16x32_bf16 v[40:43], v[186:189], v[210:213], v[40:43]
	v_mfma_f32_16x16x32_bf16 v[36:39], v[178:181], v[218:221], v[36:39]
	v_mfma_f32_16x16x32_bf16 v[32:35], v[186:189], v[218:221], v[32:35]
	s_barrier
; #define PG8_STAGE(bufoff, gbase, voff) do { _Pragma("unroll") for (int _i = 0; _i < 2; ++_i) \
;         __builtin_amdgcn_global_load_lds((const unsigned*)((const char*)(gbase) + (voff)[_i]), (LAS unsigned*)(lds + (bufoff) + ldsw + _i * 8192), 16, 0, 0); } while (0)
; #define PG8_LDA(dst, b, h) do { _Pragma("unroll") for (int m = 0; m < 4; ++m) _Pragma("unroll") for (int k = 0; k < 2; ++k) dst[m][k] = *(const LAS bf16x8*)(lds + PG8_SA(b, h) + aoff + m * 2048 + k * 1024); } while (0)
; #define PG8_MMA(ai, bj, At, Bt) do { __builtin_amdgcn_s_setprio(1); _Pragma("unroll") for (int m = 0; m < 4; ++m) _Pragma("unroll") for (int n = 0; n < 2; ++n) _Pragma("unroll") for (int k = 0; k < 2; ++k) \
;         acc[ai][bj][m][n] = __builtin_amdgcn_mfma_f32_16x16x32_bf16(Bt[n][k], At[m][k], acc[ai][bj][m][n], 0, 0, 0); __builtin_amdgcn_s_setprio(0); } while (0)
; #define PG8_WAIT_V(n) asm volatile("s_waitcnt vmcnt(" #n ")" ::: "memory")
; #define PG8_WAIT_L(n) asm volatile("s_waitcnt lgkmcnt(" #n ")" ::: "memory")
; #define PG8_BAR __builtin_amdgcn_s_barrier()
; #define PG8_SCHED __builtin_amdgcn_sched_barrier(0)
; __device__ __forceinline__ void gemm_phase(LAS unsigned char* lds, const Params& p, const bf16_t* gA, const bf16_t* gBt, const int gM, const int gN, const int gK, const int epi, const int perm, bf16_t* const Hp, const int goff, const float coef) {
;     ...
;             PG8_LDA(At, 1, 1); PG8_STAGE(PG8_SB(1, 0), b3, voffB); PG8_STAGE(PG8_SB(1, 1), b3 + hstep, voffB); PG8_STAGE(PG8_SA(1, 0), a3, voffA);
;             PG8_WAIT_V(8); PG8_WAIT_L(0); PG8_BAR; PG8_MMA(1, 0, At, B0); PG8_MMA(1, 1, At, B1); PG8_BAR; PG8_SCHED;
;         }
;         if (wr == 0) PG8_BAR;
	s_add_i32 s38, s59, s16
	v_lshl_add_u64 v[222:223], v[222:223], 0, s[12:13]
	s_mov_b32 m0, s38
	ds_read_b128 v[190:193], v169 offset:49152
	ds_read_b128 v[194:197], v169 offset:50176
	ds_read_b128 v[198:201], v169 offset:51200
	ds_read_b128 v[202:205], v169 offset:52224
	ds_read_b128 v[206:209], v169 offset:53248
	ds_read_b128 v[210:213], v169 offset:54272
	ds_read_b128 v[214:217], v169 offset:55296
	ds_read_b128 v[218:221], v169 offset:56320
	global_load_lds_dwordx4 v[222:223], off
	s_add_i32 m0, s38, 0x2000
	s_add_u32 s34, s34, 0x160080
	v_lshl_add_u64 v[222:223], v[224:225], 0, s[12:13]
	s_addc_u32 s35, s35, 0
	s_add_i32 s38, s60, s16
	global_load_lds_dwordx4 v[222:223], off
	v_lshl_add_u64 v[222:223], s[34:35], 0, v[130:131]
	s_mov_b32 m0, s38
	s_nop 0
	global_load_lds_dwordx4 v[222:223], off
	v_lshl_add_u64 v[222:223], s[34:35], 0, v[134:135]
	s_add_i32 m0, s38, 0x2000
	s_nop 0
	global_load_lds_dwordx4 v[222:223], off
	v_lshl_add_u64 v[222:223], v[226:227], 0, s[12:13]
	s_mov_b32 m0, s23
	s_nop 0
	global_load_lds_dwordx4 v[222:223], off
	v_lshl_add_u64 v[222:223], v[228:229], 0, s[12:13]
	s_mov_b32 m0, s33
	s_nop 0
	global_load_lds_dwordx4 v[222:223], off
	s_waitcnt vmcnt(8)
	s_waitcnt lgkmcnt(0)
	s_barrier
	s_waitcnt lgkmcnt(0)
	v_mfma_f32_16x16x32_bf16 v[92:95], v[146:149], v[190:193], v[92:95]
	v_mfma_f32_16x16x32_bf16 v[88:91], v[154:157], v[190:193], v[88:91]
	v_mfma_f32_16x16x32_bf16 v[84:87], v[146:149], v[198:201], v[84:87]
	v_mfma_f32_16x16x32_bf16 v[80:83], v[154:157], v[198:201], v[80:83]
	v_mfma_f32_16x16x32_bf16 v[76:79], v[146:149], v[206:209], v[76:79]
	v_mfma_f32_16x16x32_bf16 v[72:75], v[154:157], v[206:209], v[72:75]
	v_mfma_f32_16x16x32_bf16 v[64:67], v[146:149], v[214:217], v[64:67]
	v_mfma_f32_16x16x32_bf16 v[56:59], v[154:157], v[214:217], v[56:59]
	v_mfma_f32_16x16x32_bf16 v[92:95], v[150:153], v[194:197], v[92:95]
	v_mfma_f32_16x16x32_bf16 v[88:91], v[170:173], v[194:197], v[88:91]
	v_mfma_f32_16x16x32_bf16 v[84:87], v[150:153], v[202:205], v[84:87]
	v_mfma_f32_16x16x32_bf16 v[80:83], v[170:173], v[202:205], v[80:83]
	v_mfma_f32_16x16x32_bf16 v[76:79], v[150:153], v[210:213], v[76:79]
	v_mfma_f32_16x16x32_bf16 v[72:75], v[170:173], v[210:213], v[72:75]
	v_mfma_f32_16x16x32_bf16 v[64:67], v[150:153], v[218:221], v[64:67]
	v_mfma_f32_16x16x32_bf16 v[56:59], v[170:173], v[218:221], v[56:59]
	v_mfma_f32_16x16x32_bf16 v[28:31], v[174:177], v[190:193], v[28:31]
	v_mfma_f32_16x16x32_bf16 v[24:27], v[182:185], v[190:193], v[24:27]
	v_mfma_f32_16x16x32_bf16 v[20:23], v[174:177], v[198:201], v[20:23]
	v_mfma_f32_16x16x32_bf16 v[16:19], v[182:185], v[198:201], v[16:19]
	v_mfma_f32_16x16x32_bf16 v[12:15], v[174:177], v[206:209], v[12:15]
	v_mfma_f32_16x16x32_bf16 v[8:11], v[182:185], v[206:209], v[8:11]
	v_mfma_f32_16x16x32_bf16 v[4:7], v[174:177], v[214:217], v[4:7]
	v_mfma_f32_16x16x32_bf16 v[0:3], v[182:185], v[214:217], v[0:3]
	v_mfma_f32_16x16x32_bf16 v[28:31], v[178:181], v[194:197], v[28:31]
	v_mfma_f32_16x16x32_bf16 v[24:27], v[186:189], v[194:197], v[24:27]
	v_mfma_f32_16x16x32_bf16 v[20:23], v[178:181], v[202:205], v[20:23]
	v_mfma_f32_16x16x32_bf16 v[16:19], v[186:189], v[202:205], v[16:19]
	v_mfma_f32_16x16x32_bf16 v[12:15], v[178:181], v[210:213], v[12:15]
	v_mfma_f32_16x16x32_bf16 v[8:11], v[186:189], v[210:213], v[8:11]
	v_mfma_f32_16x16x32_bf16 v[4:7], v[178:181], v[218:221], v[4:7]
	v_mfma_f32_16x16x32_bf16 v[0:3], v[186:189], v[218:221], v[0:3]
	s_barrier
	s_add_u32 s30, s30, 0x100
	s_addc_u32 s31, s31, 0
	s_add_u32 s56, s56, 0x100
	s_addc_u32 s57, s57, 0
	s_cmp_ge_u32 s58, s54
	s_mov_b32 s34, s58
	s_cbranch_scc0 .LBB0_264
	s_and_b64 vcc, exec, s[24:25]
	s_cbranch_vccz .LBB0_267
	s_barrier

; #define PG8_STAGE(bufoff, gbase, voff) do { _Pragma("unroll") for (int _i = 0; _i < 2; ++_i) \
;         __builtin_amdgcn_global_load_lds((const unsigned*)((const char*)(gbase) + (voff)[_i]), (LAS unsigned*)(lds + (bufoff) + ldsw + _i * 8192), 16, 0, 0); } while (0)
; #define PG8_LDA(dst, b, h) do { _Pragma("unroll") for (int m = 0; m < 4; ++m) _Pragma("unroll") for (int k = 0; k < 2; ++k) dst[m][k] = *(const LAS bf16x8*)(lds + PG8_SA(b, h) + aoff + m * 2048 + k * 1024); } while (0)
; #define PG8_LDB(dst, b, h) do { _Pragma("unroll") for (int n = 0; n < 2; ++n) _Pragma("unroll") for (int k = 0; k < 2; ++k) dst[n][k] = *(const LAS bf16x8*)(lds + PG8_SB(b, h) + boff + n * 2048 + k * 1024); } while (0)
; #define PG8_MMA(ai, bj, At, Bt) do { __builtin_amdgcn_s_setprio(1); _Pragma("unroll") for (int m = 0; m < 4; ++m) _Pragma("unroll") for (int n = 0; n < 2; ++n) _Pragma("unroll") for (int k = 0; k < 2; ++k) \
;         acc[ai][bj][m][n] = __builtin_amdgcn_mfma_f32_16x16x32_bf16(Bt[n][k], At[m][k], acc[ai][bj][m][n], 0, 0, 0); __builtin_amdgcn_s_setprio(0); } while (0)
; #define PG8_WAIT_V(n) asm volatile("s_waitcnt vmcnt(" #n ")" ::: "memory")
; #define PG8_WAIT_L(n) asm volatile("s_waitcnt lgkmcnt(" #n ")" ::: "memory")
; #define PG8_BAR __builtin_amdgcn_s_barrier()
; #define PG8_SCHED __builtin_amdgcn_sched_barrier(0)
; __device__ __forceinline__ void gemm_phase(LAS unsigned char* lds, const Params& p, const bf16_t* gA, const bf16_t* gBt, const int gM, const int gN, const int gK, const int epi, const int perm, bf16_t* const Hp, const int goff, const float coef) {
;     ...
;         for (int t = 0; t < nt; t += 2) {
;             const bool last = (t == nt - 2);
;             const char* a1 = cA + (size_t)(t + 1) * kstep;
;             const char* a2 = last ? nA : cA + (size_t)(t + 2) * kstep; const char* b2 = last ? nB : cB + (size_t)(t + 2) * kstep;
;             const char* a3 = a2 + kstep; const char* b3 = b2 + kstep;
;             PG8_LDB(B0, 0, 0); PG8_LDB(B1, 0, 1); PG8_SCHED; PG8_LDA(At, 0, 0); PG8_STAGE(PG8_SA(1, 1), a1 + hstep, voffA);
;             PG8_WAIT_V(8); PG8_WAIT_L(0); PG8_BAR; PG8_MMA(0, 0, At, B0); PG8_MMA(0, 1, At, B1); PG8_BAR; PG8_SCHED;
;             PG8_LDA(At, 0, 1); PG8_STAGE(PG8_SB(0, 0), b2, voffB); PG8_STAGE(PG8_SB(0, 1), b2 + hstep, voffB); PG8_STAGE(PG8_SA(0, 0), a2, voffA);
.LBB0_436:
	ds_read_b128 v[128:131], v180
	ds_read_b128 v[132:135], v180 offset:1024
	ds_read_b128 v[136:139], v180 offset:2048
	ds_read_b128 v[184:187], v180 offset:3072
	ds_read_b128 v[188:191], v181
	ds_read_b128 v[192:195], v181 offset:1024
	ds_read_b128 v[196:199], v181 offset:2048
	ds_read_b128 v[200:203], v181 offset:3072
	s_add_i32 s37, s45, 2
	s_add_u32 s4, s0, 0xfff80080
	s_addc_u32 s5, s1, -1
	s_cmp_eq_u32 s23, s45
	s_cselect_b32 s49, s14, s5
	s_cselect_b32 s48, s15, s4
	s_cselect_b32 s5, s16, s35
	s_cselect_b32 s4, s17, s33
	v_lshl_add_u64 v[168:169], s[0:1], 0, v[160:161]
	s_add_i32 m0, s47, 0xc000
	ds_read_b128 v[204:207], v182
	ds_read_b128 v[208:211], v182 offset:1024
	ds_read_b128 v[212:215], v182 offset:2048
	ds_read_b128 v[216:219], v182 offset:3072
	ds_read_b128 v[220:223], v182 offset:4096
	ds_read_b128 v[224:227], v182 offset:5120
	ds_read_b128 v[228:231], v182 offset:6144
	ds_read_b128 v[232:235], v182 offset:7168
	global_load_lds_dwordx4 v[168:169], off
	v_lshl_add_u64 v[168:169], s[0:1], 0, v[162:163]
	s_add_i32 m0, s47, 0xe000
	s_nop 0
	global_load_lds_dwordx4 v[168:169], off
	s_waitcnt vmcnt(8)
	s_waitcnt lgkmcnt(0)
	s_barrier
	s_waitcnt lgkmcnt(0)
	v_mfma_f32_16x16x32_bf16 v[124:127], v[128:131], v[204:207], v[124:127]
	v_mfma_f32_16x16x32_bf16 v[120:123], v[136:139], v[204:207], v[120:123]
	v_mfma_f32_16x16x32_bf16 v[108:111], v[128:131], v[212:215], v[108:111]
	v_mfma_f32_16x16x32_bf16 v[104:107], v[136:139], v[212:215], v[104:107]
	v_mfma_f32_16x16x32_bf16 v[92:95], v[128:131], v[220:223], v[92:95]
	v_mfma_f32_16x16x32_bf16 v[88:91], v[136:139], v[220:223], v[88:91]
	v_mfma_f32_16x16x32_bf16 v[76:79], v[128:131], v[228:231], v[76:79]
	v_mfma_f32_16x16x32_bf16 v[72:75], v[136:139], v[228:231], v[72:75]
	v_mfma_f32_16x16x32_bf16 v[124:127], v[132:135], v[208:211], v[124:127]
	v_mfma_f32_16x16x32_bf16 v[120:123], v[184:187], v[208:211], v[120:123]
	v_mfma_f32_16x16x32_bf16 v[108:111], v[132:135], v[216:219], v[108:111]
	v_mfma_f32_16x16x32_bf16 v[104:107], v[184:187], v[216:219], v[104:107]
	v_mfma_f32_16x16x32_bf16 v[92:95], v[132:135], v[224:227], v[92:95]
	v_mfma_f32_16x16x32_bf16 v[88:91], v[184:187], v[224:227], v[88:91]
	v_mfma_f32_16x16x32_bf16 v[76:79], v[132:135], v[232:235], v[76:79]
	v_mfma_f32_16x16x32_bf16 v[72:75], v[184:187], v[232:235], v[72:75]
	v_mfma_f32_16x16x32_bf16 v[116:119], v[188:191], v[204:207], v[116:119]
	v_mfma_f32_16x16x32_bf16 v[112:115], v[196:199], v[204:207], v[112:115]
	v_mfma_f32_16x16x32_bf16 v[100:103], v[188:191], v[212:215], v[100:103]
	v_mfma_f32_16x16x32_bf16 v[96:99], v[196:199], v[212:215], v[96:99]
	v_mfma_f32_16x16x32_bf16 v[84:87], v[188:191], v[220:223], v[84:87]
	v_mfma_f32_16x16x32_bf16 v[80:83], v[196:199], v[220:223], v[80:83]
	v_mfma_f32_16x16x32_bf16 v[68:71], v[188:191], v[228:231], v[68:71]
	v_mfma_f32_16x16x32_bf16 v[64:67], v[196:199], v[228:231], v[64:67]
	v_mfma_f32_16x16x32_bf16 v[116:119], v[192:195], v[208:211], v[116:119]
	v_mfma_f32_16x16x32_bf16 v[112:115], v[200:203], v[208:211], v[112:115]
	v_mfma_f32_16x16x32_bf16 v[100:103], v[192:195], v[216:219], v[100:103]
	v_mfma_f32_16x16x32_bf16 v[96:99], v[200:203], v[216:219], v[96:99]
	v_mfma_f32_16x16x32_bf16 v[84:87], v[192:195], v[224:227], v[84:87]
	v_mfma_f32_16x16x32_bf16 v[80:83], v[200:203], v[224:227], v[80:83]
	v_mfma_f32_16x16x32_bf16 v[68:71], v[192:195], v[232:235], v[68:71]
	v_mfma_f32_16x16x32_bf16 v[64:67], v[200:203], v[232:235], v[64:67]
	s_barrier
	s_add_i32 s45, s19, s52
	v_lshl_add_u64 v[168:169], s[4:5], 0, v[144:145]
	s_mov_b32 m0, s45
	ds_read_b128 v[204:207], v182 offset:16384
	ds_read_b128 v[208:211], v182 offset:17408
	ds_read_b128 v[212:215], v182 offset:18432
	ds_read_b128 v[216:219], v182 offset:19456
	ds_read_b128 v[220:223], v182 offset:20480
	ds_read_b128 v[224:227], v182 offset:21504
	ds_read_b128 v[228:231], v182 offset:22528
	ds_read_b128 v[232:235], v182 offset:23552
	global_load_lds_dwordx4 v[168:169], off
	s_add_i32 m0, s45, 0x2000
	s_add_u32 s50, s4, 0x80000
	v_lshl_add_u64 v[236:237], s[4:5], 0, v[148:149]
	s_addc_u32 s51, s5, 0
	s_add_i32 s45, s21, s52
	global_load_lds_dwordx4 v[236:237], off
	v_lshl_add_u64 v[238:239], s[50:51], 0, v[144:145]
	s_mov_b32 m0, s45
	v_lshl_add_u64 v[240:241], s[48:49], 0, v[146:147]
	global_load_lds_dwordx4 v[238:239], off
	v_lshl_add_u64 v[238:239], s[50:51], 0, v[148:149]
	s_add_i32 m0, s45, 0x2000
	s_nop 0
	global_load_lds_dwordx4 v[238:239], off
	v_lshl_add_u64 v[238:239], s[48:49], 0, v[142:143]
	s_mov_b32 m0, s47
	s_nop 0
	global_load_lds_dwordx4 v[238:239], off
	s_mov_b32 m0, s53
	s_nop 0
	global_load_lds_dwordx4 v[240:241], off
	s_waitcnt vmcnt(8)
	s_waitcnt lgkmcnt(0)
	s_barrier
; #define PG8_STAGE(bufoff, gbase, voff) do { _Pragma("unroll") for (int _i = 0; _i < 2; ++_i) \
;         __builtin_amdgcn_global_load_lds((const unsigned*)((const char*)(gbase) + (voff)[_i]), (LAS unsigned*)(lds + (bufoff) + ldsw + _i * 8192), 16, 0, 0); } while (0)
; #define PG8_LDA(dst, b, h) do { _Pragma("unroll") for (int m = 0; m < 4; ++m) _Pragma("unroll") for (int k = 0; k < 2; ++k) dst[m][k] = *(const LAS bf16x8*)(lds + PG8_SA(b, h) + aoff + m * 2048 + k * 1024); } while (0)
; #define PG8_LDB(dst, b, h) do { _Pragma("unroll") for (int n = 0; n < 2; ++n) _Pragma("unroll") for (int k = 0; k < 2; ++k) dst[n][k] = *(const LAS bf16x8*)(lds + PG8_SB(b, h) + boff + n * 2048 + k * 1024); } while (0)
; #define PG8_MMA(ai, bj, At, Bt) do { __builtin_amdgcn_s_setprio(1); _Pragma("unroll") for (int m = 0; m < 4; ++m) _Pragma("unroll") for (int n = 0; n < 2; ++n) _Pragma("unroll") for (int k = 0; k < 2; ++k) \
;         acc[ai][bj][m][n] = __builtin_amdgcn_mfma_f32_16x16x32_bf16(Bt[n][k], At[m][k], acc[ai][bj][m][n], 0, 0, 0); __builtin_amdgcn_s_setprio(0); } while (0)
; #define PG8_WAIT_V(n) asm volatile("s_waitcnt vmcnt(" #n ")" ::: "memory")
; #define PG8_WAIT_L(n) asm volatile("s_waitcnt lgkmcnt(" #n ")" ::: "memory")
; #define PG8_BAR __builtin_amdgcn_s_barrier()
; #define PG8_SCHED __builtin_amdgcn_sched_barrier(0)
; __device__ __forceinline__ void gemm_phase(LAS unsigned char* lds, const Params& p, const bf16_t* gA, const bf16_t* gBt, const int gM, const int gN, const int gK, const int epi, const int perm, bf16_t* const Hp, const int goff, const float coef) {
;     ...
;             PG8_WAIT_V(8); PG8_WAIT_L(0); PG8_BAR; PG8_MMA(1, 0, At, B0); PG8_MMA(1, 1, At, B1); PG8_BAR; PG8_SCHED;
;             PG8_LDB(B0, 1, 0); PG8_LDB(B1, 1, 1); PG8_SCHED; PG8_LDA(At, 1, 0); PG8_STAGE(PG8_SA(0, 1), a2 + hstep, voffA);
;             PG8_WAIT_V(8); PG8_WAIT_L(0); PG8_BAR; PG8_MMA(0, 0, At, B0); PG8_MMA(0, 1, At, B1); PG8_BAR; PG8_SCHED;
	s_waitcnt lgkmcnt(0)
	v_mfma_f32_16x16x32_bf16 v[60:63], v[128:131], v[204:207], v[60:63]
	v_mfma_f32_16x16x32_bf16 v[56:59], v[136:139], v[204:207], v[56:59]
	v_mfma_f32_16x16x32_bf16 v[44:47], v[128:131], v[212:215], v[44:47]
	v_mfma_f32_16x16x32_bf16 v[40:43], v[136:139], v[212:215], v[40:43]
	v_mfma_f32_16x16x32_bf16 v[28:31], v[128:131], v[220:223], v[28:31]
	v_mfma_f32_16x16x32_bf16 v[24:27], v[136:139], v[220:223], v[24:27]
	v_mfma_f32_16x16x32_bf16 v[12:15], v[128:131], v[228:231], v[12:15]
	v_mfma_f32_16x16x32_bf16 v[8:11], v[136:139], v[228:231], v[8:11]
	v_mfma_f32_16x16x32_bf16 v[60:63], v[132:135], v[208:211], v[60:63]
	v_mfma_f32_16x16x32_bf16 v[56:59], v[184:187], v[208:211], v[56:59]
	v_mfma_f32_16x16x32_bf16 v[44:47], v[132:135], v[216:219], v[44:47]
	v_mfma_f32_16x16x32_bf16 v[40:43], v[184:187], v[216:219], v[40:43]
	v_mfma_f32_16x16x32_bf16 v[28:31], v[132:135], v[224:227], v[28:31]
	v_mfma_f32_16x16x32_bf16 v[24:27], v[184:187], v[224:227], v[24:27]
	v_mfma_f32_16x16x32_bf16 v[12:15], v[132:135], v[232:235], v[12:15]
	v_mfma_f32_16x16x32_bf16 v[8:11], v[184:187], v[232:235], v[8:11]
	v_mfma_f32_16x16x32_bf16 v[52:55], v[188:191], v[204:207], v[52:55]
	v_mfma_f32_16x16x32_bf16 v[48:51], v[196:199], v[204:207], v[48:51]
	v_mfma_f32_16x16x32_bf16 v[36:39], v[188:191], v[212:215], v[36:39]
	v_mfma_f32_16x16x32_bf16 v[32:35], v[196:199], v[212:215], v[32:35]
	v_mfma_f32_16x16x32_bf16 v[20:23], v[188:191], v[220:223], v[20:23]
	v_mfma_f32_16x16x32_bf16 v[16:19], v[196:199], v[220:223], v[16:19]
	v_mfma_f32_16x16x32_bf16 v[4:7], v[188:191], v[228:231], v[4:7]
	v_mfma_f32_16x16x32_bf16 v[0:3], v[196:199], v[228:231], v[0:3]
	v_mfma_f32_16x16x32_bf16 v[52:55], v[192:195], v[208:211], v[52:55]
	v_mfma_f32_16x16x32_bf16 v[48:51], v[200:203], v[208:211], v[48:51]
	v_mfma_f32_16x16x32_bf16 v[36:39], v[192:195], v[216:219], v[36:39]
	v_mfma_f32_16x16x32_bf16 v[32:35], v[200:203], v[216:219], v[32:35]
	v_mfma_f32_16x16x32_bf16 v[20:23], v[192:195], v[224:227], v[20:23]
	v_mfma_f32_16x16x32_bf16 v[16:19], v[200:203], v[224:227], v[16:19]
	v_mfma_f32_16x16x32_bf16 v[4:7], v[192:195], v[232:235], v[4:7]
	v_mfma_f32_16x16x32_bf16 v[0:3], v[200:203], v[232:235], v[0:3]
	s_barrier
	s_add_i32 s45, 0, 0x18000
	v_add_u32_e32 v150, s45, v171
	s_add_i32 s50, 0, 0x1c000
	ds_read_b128 v[128:131], v150
	ds_read_b128 v[132:135], v150 offset:1024
	ds_read_b128 v[136:139], v150 offset:2048
	ds_read_b128 v[184:187], v150 offset:3072
	v_add_u32_e32 v150, s50, v171
	ds_read_b128 v[188:191], v150
	ds_read_b128 v[192:195], v150 offset:1024
	ds_read_b128 v[196:199], v150 offset:2048
	ds_read_b128 v[200:203], v150 offset:3072
	s_add_u32 s48, s48, 0x80000
	s_addc_u32 s49, s49, 0
	s_mov_b32 m0, s54
	v_lshl_add_u64 v[242:243], s[48:49], 0, v[142:143]
	ds_read_b128 v[204:207], v182 offset:32768
	ds_read_b128 v[208:211], v182 offset:33792
	ds_read_b128 v[212:215], v182 offset:34816
	ds_read_b128 v[216:219], v182 offset:35840
	ds_read_b128 v[220:223], v182 offset:36864
	ds_read_b128 v[224:227], v182 offset:37888
	ds_read_b128 v[228:231], v182 offset:38912
	ds_read_b128 v[232:235], v182 offset:39936
	global_load_lds_dwordx4 v[242:243], off
	v_lshl_add_u64 v[242:243], s[48:49], 0, v[146:147]
	s_mov_b32 m0, s55
	s_nop 0
	global_load_lds_dwordx4 v[242:243], off
	s_waitcnt vmcnt(8)
	s_waitcnt lgkmcnt(0)
	s_barrier
	s_waitcnt lgkmcnt(0)
	v_mfma_f32_16x16x32_bf16 v[124:127], v[128:131], v[204:207], v[124:127]
	v_mfma_f32_16x16x32_bf16 v[120:123], v[136:139], v[204:207], v[120:123]
	v_mfma_f32_16x16x32_bf16 v[108:111], v[128:131], v[212:215], v[108:111]
	v_mfma_f32_16x16x32_bf16 v[104:107], v[136:139], v[212:215], v[104:107]
	v_mfma_f32_16x16x32_bf16 v[92:95], v[128:131], v[220:223], v[92:95]
	v_mfma_f32_16x16x32_bf16 v[88:91], v[136:139], v[220:223], v[88:91]
	v_mfma_f32_16x16x32_bf16 v[76:79], v[128:131], v[228:231], v[76:79]
	v_mfma_f32_16x16x32_bf16 v[72:75], v[136:139], v[228:231], v[72:75]
	v_mfma_f32_16x16x32_bf16 v[124:127], v[132:135], v[208:211], v[124:127]
	v_mfma_f32_16x16x32_bf16 v[120:123], v[184:187], v[208:211], v[120:123]
	v_mfma_f32_16x16x32_bf16 v[108:111], v[132:135], v[216:219], v[108:111]
	v_mfma_f32_16x16x32_bf16 v[104:107], v[184:187], v[216:219], v[104:107]
	v_mfma_f32_16x16x32_bf16 v[92:95], v[132:135], v[224:227], v[92:95]
	v_mfma_f32_16x16x32_bf16 v[88:91], v[184:187], v[224:227], v[88:91]
	v_mfma_f32_16x16x32_bf16 v[76:79], v[132:135], v[232:235], v[76:79]
	v_mfma_f32_16x16x32_bf16 v[72:75], v[184:187], v[232:235], v[72:75]
	v_mfma_f32_16x16x32_bf16 v[116:119], v[188:191], v[204:207], v[116:119]
	v_mfma_f32_16x16x32_bf16 v[112:115], v[196:199], v[204:207], v[112:115]
	v_mfma_f32_16x16x32_bf16 v[100:103], v[188:191], v[212:215], v[100:103]
	v_mfma_f32_16x16x32_bf16 v[96:99], v[196:199], v[212:215], v[96:99]
	v_mfma_f32_16x16x32_bf16 v[84:87], v[188:191], v[220:223], v[84:87]
	v_mfma_f32_16x16x32_bf16 v[80:83], v[196:199], v[220:223], v[80:83]
	v_mfma_f32_16x16x32_bf16 v[68:71], v[188:191], v[228:231], v[68:71]
	v_mfma_f32_16x16x32_bf16 v[64:67], v[196:199], v[228:231], v[64:67]
	v_mfma_f32_16x16x32_bf16 v[116:119], v[192:195], v[208:211], v[116:119]
	v_mfma_f32_16x16x32_bf16 v[112:115], v[200:203], v[208:211], v[112:115]
	v_mfma_f32_16x16x32_bf16 v[100:103], v[192:195], v[216:219], v[100:103]
	v_mfma_f32_16x16x32_bf16 v[96:99], v[200:203], v[216:219], v[96:99]
	v_mfma_f32_16x16x32_bf16 v[84:87], v[192:195], v[224:227], v[84:87]
	v_mfma_f32_16x16x32_bf16 v[80:83], v[200:203], v[224:227], v[80:83]
	v_mfma_f32_16x16x32_bf16 v[68:71], v[192:195], v[232:235], v[68:71]
	v_mfma_f32_16x16x32_bf16 v[64:67], v[200:203], v[232:235], v[64:67]
	s_barrier
; #define PG8_STAGE(bufoff, gbase, voff) do { _Pragma("unroll") for (int _i = 0; _i < 2; ++_i) \
;         __builtin_amdgcn_global_load_lds((const unsigned*)((const char*)(gbase) + (voff)[_i]), (LAS unsigned*)(lds + (bufoff) + ldsw + _i * 8192), 16, 0, 0); } while (0)
; #define PG8_LDA(dst, b, h) do { _Pragma("unroll") for (int m = 0; m < 4; ++m) _Pragma("unroll") for (int k = 0; k < 2; ++k) dst[m][k] = *(const LAS bf16x8*)(lds + PG8_SA(b, h) + aoff + m * 2048 + k * 1024); } while (0)
; #define PG8_MMA(ai, bj, At, Bt) do { __builtin_amdgcn_s_setprio(1); _Pragma("unroll") for (int m = 0; m < 4; ++m) _Pragma("unroll") for (int n = 0; n < 2; ++n) _Pragma("unroll") for (int k = 0; k < 2; ++k) \
;         acc[ai][bj][m][n] = __builtin_amdgcn_mfma_f32_16x16x32_bf16(Bt[n][k], At[m][k], acc[ai][bj][m][n], 0, 0, 0); __builtin_amdgcn_s_setprio(0); } while (0)
; #define PG8_WAIT_V(n) asm volatile("s_waitcnt vmcnt(" #n ")" ::: "memory")
; #define PG8_WAIT_L(n) asm volatile("s_waitcnt lgkmcnt(" #n ")" ::: "memory")
; #define PG8_BAR __builtin_amdgcn_s_barrier()
; #define PG8_SCHED __builtin_amdgcn_sched_barrier(0)
; __device__ __forceinline__ void gemm_epilogue(const Params& p, const int epi, bf16_t* const Hp, const int goff, const float coef, const f32x4 (&acc)[2][2][4][2], const pg8::Unit& u, int wr, int wc, int fr, int fq) {
;     ...
;         const int seg = u.pn >> 2;
;         const bool lat = u.pm < 128;
;         if (seg < 5) {
; __device__ __forceinline__ void gemm_phase(LAS unsigned char* lds, const Params& p, const bf16_t* gA, const bf16_t* gBt, const int gM, const int gN, const int gK, const int epi, const int perm, bf16_t* const Hp, const int goff, const float coef) {
;     ...
;             PG8_LDA(At, 1, 1); PG8_STAGE(PG8_SB(1, 0), b3, voffB); PG8_STAGE(PG8_SB(1, 1), b3 + hstep, voffB); PG8_STAGE(PG8_SA(1, 0), a3, voffA);
;             PG8_WAIT_V(8); PG8_WAIT_L(0); PG8_BAR; PG8_MMA(1, 0, At, B0); PG8_MMA(1, 1, At, B1); PG8_BAR; PG8_SCHED;
;         }
;         if (wr == 0) PG8_BAR;
	s_add_i32 s45, s45, s52
	v_lshl_add_u64 v[168:169], v[168:169], 0, s[10:11]
	s_mov_b32 m0, s45
	ds_read_b128 v[204:207], v182 offset:49152
	ds_read_b128 v[208:211], v182 offset:50176
	ds_read_b128 v[212:215], v182 offset:51200
	ds_read_b128 v[216:219], v182 offset:52224
	ds_read_b128 v[220:223], v182 offset:53248
	ds_read_b128 v[224:227], v182 offset:54272
	ds_read_b128 v[228:231], v182 offset:55296
	ds_read_b128 v[232:235], v182 offset:56320
	global_load_lds_dwordx4 v[168:169], off
	s_add_i32 m0, s45, 0x2000
	s_add_u32 s4, s4, 0x80080
	v_lshl_add_u64 v[168:169], v[236:237], 0, s[10:11]
	s_addc_u32 s5, s5, 0
	s_add_i32 s45, s50, s52
	global_load_lds_dwordx4 v[168:169], off
	v_lshl_add_u64 v[168:169], s[4:5], 0, v[144:145]
	s_mov_b32 m0, s45
	s_nop 0
	global_load_lds_dwordx4 v[168:169], off
	v_lshl_add_u64 v[168:169], s[4:5], 0, v[148:149]
	s_add_i32 m0, s45, 0x2000
	s_nop 0
	global_load_lds_dwordx4 v[168:169], off
	v_lshl_add_u64 v[168:169], v[238:239], 0, s[10:11]
	s_mov_b32 m0, s57
	s_nop 0
	global_load_lds_dwordx4 v[168:169], off
	v_lshl_add_u64 v[168:169], v[240:241], 0, s[10:11]
	s_mov_b32 m0, s58
	s_nop 0
	global_load_lds_dwordx4 v[168:169], off
	s_waitcnt vmcnt(8)
	s_waitcnt lgkmcnt(0)
	s_barrier
	s_waitcnt lgkmcnt(0)
	v_mfma_f32_16x16x32_bf16 v[60:63], v[128:131], v[204:207], v[60:63]
	v_mfma_f32_16x16x32_bf16 v[56:59], v[136:139], v[204:207], v[56:59]
	v_mfma_f32_16x16x32_bf16 v[44:47], v[128:131], v[212:215], v[44:47]
	v_mfma_f32_16x16x32_bf16 v[40:43], v[136:139], v[212:215], v[40:43]
	v_mfma_f32_16x16x32_bf16 v[28:31], v[128:131], v[220:223], v[28:31]
	v_mfma_f32_16x16x32_bf16 v[24:27], v[136:139], v[220:223], v[24:27]
	v_mfma_f32_16x16x32_bf16 v[12:15], v[128:131], v[228:231], v[12:15]
	v_mfma_f32_16x16x32_bf16 v[8:11], v[136:139], v[228:231], v[8:11]
	v_mfma_f32_16x16x32_bf16 v[60:63], v[132:135], v[208:211], v[60:63]
	v_mfma_f32_16x16x32_bf16 v[56:59], v[184:187], v[208:211], v[56:59]
	v_mfma_f32_16x16x32_bf16 v[44:47], v[132:135], v[216:219], v[44:47]
	v_mfma_f32_16x16x32_bf16 v[40:43], v[184:187], v[216:219], v[40:43]
	v_mfma_f32_16x16x32_bf16 v[28:31], v[132:135], v[224:227], v[28:31]
	v_mfma_f32_16x16x32_bf16 v[24:27], v[184:187], v[224:227], v[24:27]
	v_mfma_f32_16x16x32_bf16 v[12:15], v[132:135], v[232:235], v[12:15]
	v_mfma_f32_16x16x32_bf16 v[8:11], v[184:187], v[232:235], v[8:11]
	v_mfma_f32_16x16x32_bf16 v[52:55], v[188:191], v[204:207], v[52:55]
	v_mfma_f32_16x16x32_bf16 v[48:51], v[196:199], v[204:207], v[48:51]
	v_mfma_f32_16x16x32_bf16 v[36:39], v[188:191], v[212:215], v[36:39]
	v_mfma_f32_16x16x32_bf16 v[32:35], v[196:199], v[212:215], v[32:35]
	v_mfma_f32_16x16x32_bf16 v[20:23], v[188:191], v[220:223], v[20:23]
	v_mfma_f32_16x16x32_bf16 v[16:19], v[196:199], v[220:223], v[16:19]
	v_mfma_f32_16x16x32_bf16 v[4:7], v[188:191], v[228:231], v[4:7]
	v_mfma_f32_16x16x32_bf16 v[0:3], v[196:199], v[228:231], v[0:3]
	v_mfma_f32_16x16x32_bf16 v[52:55], v[192:195], v[208:211], v[52:55]
	v_mfma_f32_16x16x32_bf16 v[48:51], v[200:203], v[208:211], v[48:51]
	v_mfma_f32_16x16x32_bf16 v[36:39], v[192:195], v[216:219], v[36:39]
	v_mfma_f32_16x16x32_bf16 v[32:35], v[200:203], v[216:219], v[32:35]
	v_mfma_f32_16x16x32_bf16 v[20:23], v[192:195], v[224:227], v[20:23]
	v_mfma_f32_16x16x32_bf16 v[16:19], v[200:203], v[224:227], v[16:19]
	v_mfma_f32_16x16x32_bf16 v[4:7], v[192:195], v[232:235], v[4:7]
	v_mfma_f32_16x16x32_bf16 v[0:3], v[200:203], v[232:235], v[0:3]
	s_barrier
	s_add_u32 s0, s0, 0x100
	s_addc_u32 s1, s1, 0
	s_add_u32 s33, s33, 0x100
	s_addc_u32 s35, s35, 0
	s_cmp_ge_u32 s37, s22
	s_mov_b32 s45, s37
	s_cbranch_scc0 .LBB0_436
	s_and_b64 vcc, exec, s[12:13]
	s_cbranch_vccnz .LBB0_440
	s_ashr_i32 s14, s46, 2
	s_cmp_gt_i32 s14, 4
	s_mov_b64 s[0:1], -1
	s_cbranch_scc1 .LBB0_441

; #define PG8_STAGE(bufoff, gbase, voff) do { _Pragma("unroll") for (int _i = 0; _i < 2; ++_i) \
;         __builtin_amdgcn_global_load_lds((const unsigned*)((const char*)(gbase) + (voff)[_i]), (LAS unsigned*)(lds + (bufoff) + ldsw + _i * 8192), 16, 0, 0); } while (0)
; #define PG8_LDA(dst, b, h) do { _Pragma("unroll") for (int m = 0; m < 4; ++m) _Pragma("unroll") for (int k = 0; k < 2; ++k) dst[m][k] = *(const LAS bf16x8*)(lds + PG8_SA(b, h) + aoff + m * 2048 + k * 1024); } while (0)
; #define PG8_LDB(dst, b, h) do { _Pragma("unroll") for (int n = 0; n < 2; ++n) _Pragma("unroll") for (int k = 0; k < 2; ++k) dst[n][k] = *(const LAS bf16x8*)(lds + PG8_SB(b, h) + boff + n * 2048 + k * 1024); } while (0)
; #define PG8_MMA(ai, bj, At, Bt) do { __builtin_amdgcn_s_setprio(1); _Pragma("unroll") for (int m = 0; m < 4; ++m) _Pragma("unroll") for (int n = 0; n < 2; ++n) _Pragma("unroll") for (int k = 0; k < 2; ++k) \
;         acc[ai][bj][m][n] = __builtin_amdgcn_mfma_f32_16x16x32_bf16(Bt[n][k], At[m][k], acc[ai][bj][m][n], 0, 0, 0); __builtin_amdgcn_s_setprio(0); } while (0)
; #define PG8_WAIT_V(n) asm volatile("s_waitcnt vmcnt(" #n ")" ::: "memory")
; #define PG8_WAIT_L(n) asm volatile("s_waitcnt lgkmcnt(" #n ")" ::: "memory")
; #define PG8_BAR __builtin_amdgcn_s_barrier()
; #define PG8_SCHED __builtin_amdgcn_sched_barrier(0)
; __device__ __forceinline__ void gemm_phase(LAS unsigned char* lds, const Params& p, const bf16_t* gA, const bf16_t* gBt, const int gM, const int gN, const int gK, const int epi, const int perm, bf16_t* const Hp, const int goff, const float coef) {
;     ...
;             const bool last = (t == nt - 2);
;             const char* a1 = cA + (size_t)(t + 1) * kstep;
;             const char* a2 = last ? nA : cA + (size_t)(t + 2) * kstep; const char* b2 = last ? nB : cB + (size_t)(t + 2) * kstep;
;             const char* a3 = a2 + kstep; const char* b3 = b2 + kstep;
;             PG8_LDB(B0, 0, 0); PG8_LDB(B1, 0, 1); PG8_SCHED; PG8_LDA(At, 0, 0); PG8_STAGE(PG8_SA(1, 1), a1 + hstep, voffA);
;             PG8_WAIT_V(8); PG8_WAIT_L(0); PG8_BAR; PG8_MMA(0, 0, At, B0); PG8_MMA(0, 1, At, B1); PG8_BAR; PG8_SCHED;
;             PG8_LDA(At, 0, 1); PG8_STAGE(PG8_SB(0, 0), b2, voffB); PG8_STAGE(PG8_SB(0, 1), b2 + hstep, voffB); PG8_STAGE(PG8_SA(0, 0), a2, voffA);
.LBB0_1593:
	ds_read_b128 v[128:131], v174
	ds_read_b128 v[132:135], v174 offset:1024
	ds_read_b128 v[152:155], v174 offset:2048
	ds_read_b128 v[156:159], v174 offset:3072
	ds_read_b128 v[160:163], v175
	ds_read_b128 v[178:181], v175 offset:1024
	ds_read_b128 v[182:185], v175 offset:2048
	ds_read_b128 v[186:189], v175 offset:3072
	s_add_i32 s56, s30, 2
	s_add_u32 s28, s26, 0xfff80080
	s_addc_u32 s29, s27, -1
	s_cmp_eq_u32 s53, s30
	s_cselect_b32 s30, s19, s28
	s_cselect_b32 s31, s13, s29
	s_cselect_b32 s29, s15, s55
	s_cselect_b32 s28, s25, s54
	v_lshl_add_u64 v[222:223], s[26:27], 0, v[146:147]
	s_add_i32 m0, s37, 0xc000
	ds_read_b128 v[190:193], v176
	ds_read_b128 v[194:197], v176 offset:1024
	ds_read_b128 v[198:201], v176 offset:2048
	ds_read_b128 v[202:205], v176 offset:3072
	ds_read_b128 v[206:209], v176 offset:4096
	ds_read_b128 v[210:213], v176 offset:5120
	ds_read_b128 v[214:217], v176 offset:6144
	ds_read_b128 v[218:221], v176 offset:7168
	global_load_lds_dwordx4 v[222:223], off
	v_lshl_add_u64 v[222:223], s[26:27], 0, v[148:149]
	s_add_i32 m0, s37, 0xe000
	s_nop 0
	global_load_lds_dwordx4 v[222:223], off
	s_waitcnt vmcnt(8)
	s_waitcnt lgkmcnt(0)
	s_barrier
	s_waitcnt lgkmcnt(0)
	v_mfma_f32_16x16x32_bf16 v[124:127], v[128:131], v[190:193], v[124:127]
	v_mfma_f32_16x16x32_bf16 v[120:123], v[152:155], v[190:193], v[120:123]
	v_mfma_f32_16x16x32_bf16 v[116:119], v[128:131], v[198:201], v[116:119]
	v_mfma_f32_16x16x32_bf16 v[112:115], v[152:155], v[198:201], v[112:115]
	v_mfma_f32_16x16x32_bf16 v[108:111], v[128:131], v[206:209], v[108:111]
	v_mfma_f32_16x16x32_bf16 v[104:107], v[152:155], v[206:209], v[104:107]
	v_mfma_f32_16x16x32_bf16 v[100:103], v[128:131], v[214:217], v[100:103]
	v_mfma_f32_16x16x32_bf16 v[96:99], v[152:155], v[214:217], v[96:99]
	v_mfma_f32_16x16x32_bf16 v[124:127], v[132:135], v[194:197], v[124:127]
	v_mfma_f32_16x16x32_bf16 v[120:123], v[156:159], v[194:197], v[120:123]
	v_mfma_f32_16x16x32_bf16 v[116:119], v[132:135], v[202:205], v[116:119]
	v_mfma_f32_16x16x32_bf16 v[112:115], v[156:159], v[202:205], v[112:115]
	v_mfma_f32_16x16x32_bf16 v[108:111], v[132:135], v[210:213], v[108:111]
	v_mfma_f32_16x16x32_bf16 v[104:107], v[156:159], v[210:213], v[104:107]
	v_mfma_f32_16x16x32_bf16 v[100:103], v[132:135], v[218:221], v[100:103]
	v_mfma_f32_16x16x32_bf16 v[96:99], v[156:159], v[218:221], v[96:99]
	v_mfma_f32_16x16x32_bf16 v[68:71], v[160:163], v[190:193], v[68:71]
	v_mfma_f32_16x16x32_bf16 v[64:67], v[182:185], v[190:193], v[64:67]
	v_mfma_f32_16x16x32_bf16 v[52:55], v[160:163], v[198:201], v[52:55]
	v_mfma_f32_16x16x32_bf16 v[48:51], v[182:185], v[198:201], v[48:51]
	v_mfma_f32_16x16x32_bf16 v[44:47], v[160:163], v[206:209], v[44:47]
	v_mfma_f32_16x16x32_bf16 v[40:43], v[182:185], v[206:209], v[40:43]
	v_mfma_f32_16x16x32_bf16 v[36:39], v[160:163], v[214:217], v[36:39]
	v_mfma_f32_16x16x32_bf16 v[32:35], v[182:185], v[214:217], v[32:35]
	v_mfma_f32_16x16x32_bf16 v[68:71], v[178:181], v[194:197], v[68:71]
	v_mfma_f32_16x16x32_bf16 v[64:67], v[186:189], v[194:197], v[64:67]
	v_mfma_f32_16x16x32_bf16 v[52:55], v[178:181], v[202:205], v[52:55]
	v_mfma_f32_16x16x32_bf16 v[48:51], v[186:189], v[202:205], v[48:51]
	v_mfma_f32_16x16x32_bf16 v[44:47], v[178:181], v[210:213], v[44:47]
	v_mfma_f32_16x16x32_bf16 v[40:43], v[186:189], v[210:213], v[40:43]
	v_mfma_f32_16x16x32_bf16 v[36:39], v[178:181], v[218:221], v[36:39]
	v_mfma_f32_16x16x32_bf16 v[32:35], v[186:189], v[218:221], v[32:35]
	s_barrier
	s_add_i32 s57, s48, s36
	v_lshl_add_u64 v[222:223], s[28:29], 0, v[138:139]
	s_mov_b32 m0, s57
	ds_read_b128 v[190:193], v176 offset:16384
	ds_read_b128 v[194:197], v176 offset:17408
	ds_read_b128 v[198:201], v176 offset:18432
	ds_read_b128 v[202:205], v176 offset:19456
	ds_read_b128 v[206:209], v176 offset:20480
	ds_read_b128 v[210:213], v176 offset:21504
	ds_read_b128 v[214:217], v176 offset:22528
	ds_read_b128 v[218:221], v176 offset:23552
	global_load_lds_dwordx4 v[222:223], off
	s_add_i32 m0, s57, 0x2000
	s_add_u32 s58, s28, 0x80000
	v_lshl_add_u64 v[224:225], s[28:29], 0, v[144:145]
	s_addc_u32 s59, s29, 0
	s_add_i32 s57, s49, s36
	global_load_lds_dwordx4 v[224:225], off
	v_lshl_add_u64 v[226:227], s[58:59], 0, v[138:139]
	s_mov_b32 m0, s57
	v_lshl_add_u64 v[228:229], s[30:31], 0, v[142:143]
	global_load_lds_dwordx4 v[226:227], off
	v_lshl_add_u64 v[226:227], s[58:59], 0, v[144:145]
	s_add_i32 m0, s57, 0x2000
	s_nop 0
	global_load_lds_dwordx4 v[226:227], off
	v_lshl_add_u64 v[226:227], s[30:31], 0, v[136:137]
	s_mov_b32 m0, s37
	s_nop 0
	global_load_lds_dwordx4 v[226:227], off
	s_mov_b32 m0, s38
	s_nop 0
	global_load_lds_dwordx4 v[228:229], off
	s_waitcnt vmcnt(8)
	s_waitcnt lgkmcnt(0)
	s_barrier
; #define PG8_STAGE(bufoff, gbase, voff) do { _Pragma("unroll") for (int _i = 0; _i < 2; ++_i) \
;         __builtin_amdgcn_global_load_lds((const unsigned*)((const char*)(gbase) + (voff)[_i]), (LAS unsigned*)(lds + (bufoff) + ldsw + _i * 8192), 16, 0, 0); } while (0)
; #define PG8_LDA(dst, b, h) do { _Pragma("unroll") for (int m = 0; m < 4; ++m) _Pragma("unroll") for (int k = 0; k < 2; ++k) dst[m][k] = *(const LAS bf16x8*)(lds + PG8_SA(b, h) + aoff + m * 2048 + k * 1024); } while (0)
; #define PG8_LDB(dst, b, h) do { _Pragma("unroll") for (int n = 0; n < 2; ++n) _Pragma("unroll") for (int k = 0; k < 2; ++k) dst[n][k] = *(const LAS bf16x8*)(lds + PG8_SB(b, h) + boff + n * 2048 + k * 1024); } while (0)
; #define PG8_MMA(ai, bj, At, Bt) do { __builtin_amdgcn_s_setprio(1); _Pragma("unroll") for (int m = 0; m < 4; ++m) _Pragma("unroll") for (int n = 0; n < 2; ++n) _Pragma("unroll") for (int k = 0; k < 2; ++k) \
;         acc[ai][bj][m][n] = __builtin_amdgcn_mfma_f32_16x16x32_bf16(Bt[n][k], At[m][k], acc[ai][bj][m][n], 0, 0, 0); __builtin_amdgcn_s_setprio(0); } while (0)
; #define PG8_WAIT_V(n) asm volatile("s_waitcnt vmcnt(" #n ")" ::: "memory")
; #define PG8_WAIT_L(n) asm volatile("s_waitcnt lgkmcnt(" #n ")" ::: "memory")
; #define PG8_BAR __builtin_amdgcn_s_barrier()
; #define PG8_SCHED __builtin_amdgcn_sched_barrier(0)
; __device__ __forceinline__ void gemm_phase(LAS unsigned char* lds, const Params& p, const bf16_t* gA, const bf16_t* gBt, const int gM, const int gN, const int gK, const int epi, const int perm, bf16_t* const Hp, const int goff, const float coef) {
;     ...
;             PG8_WAIT_V(8); PG8_WAIT_L(0); PG8_BAR; PG8_MMA(1, 0, At, B0); PG8_MMA(1, 1, At, B1); PG8_BAR; PG8_SCHED;
;             PG8_LDB(B0, 1, 0); PG8_LDB(B1, 1, 1); PG8_SCHED; PG8_LDA(At, 1, 0); PG8_STAGE(PG8_SA(0, 1), a2 + hstep, voffA);
;             PG8_WAIT_V(8); PG8_WAIT_L(0); PG8_BAR; PG8_MMA(0, 0, At, B0); PG8_MMA(0, 1, At, B1); PG8_BAR; PG8_SCHED;
	s_waitcnt lgkmcnt(0)
	v_mfma_f32_16x16x32_bf16 v[92:95], v[128:131], v[190:193], v[92:95]
	v_mfma_f32_16x16x32_bf16 v[88:91], v[152:155], v[190:193], v[88:91]
	v_mfma_f32_16x16x32_bf16 v[84:87], v[128:131], v[198:201], v[84:87]
	v_mfma_f32_16x16x32_bf16 v[80:83], v[152:155], v[198:201], v[80:83]
	v_mfma_f32_16x16x32_bf16 v[76:79], v[128:131], v[206:209], v[76:79]
	v_mfma_f32_16x16x32_bf16 v[72:75], v[152:155], v[206:209], v[72:75]
	v_mfma_f32_16x16x32_bf16 v[60:63], v[128:131], v[214:217], v[60:63]
	v_mfma_f32_16x16x32_bf16 v[56:59], v[152:155], v[214:217], v[56:59]
	v_mfma_f32_16x16x32_bf16 v[92:95], v[132:135], v[194:197], v[92:95]
	v_mfma_f32_16x16x32_bf16 v[88:91], v[156:159], v[194:197], v[88:91]
	v_mfma_f32_16x16x32_bf16 v[84:87], v[132:135], v[202:205], v[84:87]
	v_mfma_f32_16x16x32_bf16 v[80:83], v[156:159], v[202:205], v[80:83]
	v_mfma_f32_16x16x32_bf16 v[76:79], v[132:135], v[210:213], v[76:79]
	v_mfma_f32_16x16x32_bf16 v[72:75], v[156:159], v[210:213], v[72:75]
	v_mfma_f32_16x16x32_bf16 v[60:63], v[132:135], v[218:221], v[60:63]
	v_mfma_f32_16x16x32_bf16 v[56:59], v[156:159], v[218:221], v[56:59]
	v_mfma_f32_16x16x32_bf16 v[28:31], v[160:163], v[190:193], v[28:31]
	v_mfma_f32_16x16x32_bf16 v[24:27], v[182:185], v[190:193], v[24:27]
	v_mfma_f32_16x16x32_bf16 v[20:23], v[160:163], v[198:201], v[20:23]
	v_mfma_f32_16x16x32_bf16 v[16:19], v[182:185], v[198:201], v[16:19]
	v_mfma_f32_16x16x32_bf16 v[12:15], v[160:163], v[206:209], v[12:15]
	v_mfma_f32_16x16x32_bf16 v[8:11], v[182:185], v[206:209], v[8:11]
	v_mfma_f32_16x16x32_bf16 v[4:7], v[160:163], v[214:217], v[4:7]
	v_mfma_f32_16x16x32_bf16 v[0:3], v[182:185], v[214:217], v[0:3]
	v_mfma_f32_16x16x32_bf16 v[28:31], v[178:181], v[194:197], v[28:31]
	v_mfma_f32_16x16x32_bf16 v[24:27], v[186:189], v[194:197], v[24:27]
	v_mfma_f32_16x16x32_bf16 v[20:23], v[178:181], v[202:205], v[20:23]
	v_mfma_f32_16x16x32_bf16 v[16:19], v[186:189], v[202:205], v[16:19]
	v_mfma_f32_16x16x32_bf16 v[12:15], v[178:181], v[210:213], v[12:15]
	v_mfma_f32_16x16x32_bf16 v[8:11], v[186:189], v[210:213], v[8:11]
	v_mfma_f32_16x16x32_bf16 v[4:7], v[178:181], v[218:221], v[4:7]
	v_mfma_f32_16x16x32_bf16 v[0:3], v[186:189], v[218:221], v[0:3]
	s_barrier
	s_add_i32 s57, 0, 0x18000
	v_add_u32_e32 v141, s57, v165
	s_add_i32 s58, 0, 0x1c000
	ds_read_b128 v[128:131], v141
	ds_read_b128 v[132:135], v141 offset:1024
	ds_read_b128 v[152:155], v141 offset:2048
	ds_read_b128 v[156:159], v141 offset:3072
	v_add_u32_e32 v141, s58, v165
	ds_read_b128 v[160:163], v141
	ds_read_b128 v[178:181], v141 offset:1024
	ds_read_b128 v[182:185], v141 offset:2048
	ds_read_b128 v[186:189], v141 offset:3072
	s_add_u32 s30, s30, 0x80000
	s_addc_u32 s31, s31, 0
	s_mov_b32 m0, s39
	v_lshl_add_u64 v[230:231], s[30:31], 0, v[136:137]
	ds_read_b128 v[190:193], v176 offset:32768
	ds_read_b128 v[194:197], v176 offset:33792
	ds_read_b128 v[198:201], v176 offset:34816
	ds_read_b128 v[202:205], v176 offset:35840
	ds_read_b128 v[206:209], v176 offset:36864
	ds_read_b128 v[210:213], v176 offset:37888
	ds_read_b128 v[214:217], v176 offset:38912
	ds_read_b128 v[218:221], v176 offset:39936
	global_load_lds_dwordx4 v[230:231], off
	v_lshl_add_u64 v[230:231], s[30:31], 0, v[142:143]
	s_mov_b32 m0, s40
	s_nop 0
	global_load_lds_dwordx4 v[230:231], off
	s_waitcnt vmcnt(8)
	s_waitcnt lgkmcnt(0)
	s_barrier
	s_waitcnt lgkmcnt(0)
	v_mfma_f32_16x16x32_bf16 v[124:127], v[128:131], v[190:193], v[124:127]
	v_mfma_f32_16x16x32_bf16 v[120:123], v[152:155], v[190:193], v[120:123]
	v_mfma_f32_16x16x32_bf16 v[116:119], v[128:131], v[198:201], v[116:119]
	v_mfma_f32_16x16x32_bf16 v[112:115], v[152:155], v[198:201], v[112:115]
	v_mfma_f32_16x16x32_bf16 v[108:111], v[128:131], v[206:209], v[108:111]
	v_mfma_f32_16x16x32_bf16 v[104:107], v[152:155], v[206:209], v[104:107]
	v_mfma_f32_16x16x32_bf16 v[100:103], v[128:131], v[214:217], v[100:103]
	v_mfma_f32_16x16x32_bf16 v[96:99], v[152:155], v[214:217], v[96:99]
	v_mfma_f32_16x16x32_bf16 v[124:127], v[132:135], v[194:197], v[124:127]
	v_mfma_f32_16x16x32_bf16 v[120:123], v[156:159], v[194:197], v[120:123]
	v_mfma_f32_16x16x32_bf16 v[116:119], v[132:135], v[202:205], v[116:119]
	v_mfma_f32_16x16x32_bf16 v[112:115], v[156:159], v[202:205], v[112:115]
	v_mfma_f32_16x16x32_bf16 v[108:111], v[132:135], v[210:213], v[108:111]
	v_mfma_f32_16x16x32_bf16 v[104:107], v[156:159], v[210:213], v[104:107]
	v_mfma_f32_16x16x32_bf16 v[100:103], v[132:135], v[218:221], v[100:103]
	v_mfma_f32_16x16x32_bf16 v[96:99], v[156:159], v[218:221], v[96:99]
	v_mfma_f32_16x16x32_bf16 v[68:71], v[160:163], v[190:193], v[68:71]
	v_mfma_f32_16x16x32_bf16 v[64:67], v[182:185], v[190:193], v[64:67]
	v_mfma_f32_16x16x32_bf16 v[52:55], v[160:163], v[198:201], v[52:55]
	v_mfma_f32_16x16x32_bf16 v[48:51], v[182:185], v[198:201], v[48:51]
	v_mfma_f32_16x16x32_bf16 v[44:47], v[160:163], v[206:209], v[44:47]
	v_mfma_f32_16x16x32_bf16 v[40:43], v[182:185], v[206:209], v[40:43]
	v_mfma_f32_16x16x32_bf16 v[36:39], v[160:163], v[214:217], v[36:39]
	v_mfma_f32_16x16x32_bf16 v[32:35], v[182:185], v[214:217], v[32:35]
	v_mfma_f32_16x16x32_bf16 v[68:71], v[178:181], v[194:197], v[68:71]
	v_mfma_f32_16x16x32_bf16 v[64:67], v[186:189], v[194:197], v[64:67]
	v_mfma_f32_16x16x32_bf16 v[52:55], v[178:181], v[202:205], v[52:55]
	v_mfma_f32_16x16x32_bf16 v[48:51], v[186:189], v[202:205], v[48:51]
	v_mfma_f32_16x16x32_bf16 v[44:47], v[178:181], v[210:213], v[44:47]
	v_mfma_f32_16x16x32_bf16 v[40:43], v[186:189], v[210:213], v[40:43]
	v_mfma_f32_16x16x32_bf16 v[36:39], v[178:181], v[218:221], v[36:39]
	v_mfma_f32_16x16x32_bf16 v[32:35], v[186:189], v[218:221], v[32:35]
	s_barrier
; #define PG8_STAGE(bufoff, gbase, voff) do { _Pragma("unroll") for (int _i = 0; _i < 2; ++_i) \
;         __builtin_amdgcn_global_load_lds((const unsigned*)((const char*)(gbase) + (voff)[_i]), (LAS unsigned*)(lds + (bufoff) + ldsw + _i * 8192), 16, 0, 0); } while (0)
; #define PG8_LDA(dst, b, h) do { _Pragma("unroll") for (int m = 0; m < 4; ++m) _Pragma("unroll") for (int k = 0; k < 2; ++k) dst[m][k] = *(const LAS bf16x8*)(lds + PG8_SA(b, h) + aoff + m * 2048 + k * 1024); } while (0)
; #define PG8_MMA(ai, bj, At, Bt) do { __builtin_amdgcn_s_setprio(1); _Pragma("unroll") for (int m = 0; m < 4; ++m) _Pragma("unroll") for (int n = 0; n < 2; ++n) _Pragma("unroll") for (int k = 0; k < 2; ++k) \
;         acc[ai][bj][m][n] = __builtin_amdgcn_mfma_f32_16x16x32_bf16(Bt[n][k], At[m][k], acc[ai][bj][m][n], 0, 0, 0); __builtin_amdgcn_s_setprio(0); } while (0)
; #define PG8_WAIT_V(n) asm volatile("s_waitcnt vmcnt(" #n ")" ::: "memory")
; #define PG8_WAIT_L(n) asm volatile("s_waitcnt lgkmcnt(" #n ")" ::: "memory")
; #define PG8_BAR __builtin_amdgcn_s_barrier()
; #define PG8_SCHED __builtin_amdgcn_sched_barrier(0)
; __device__ __forceinline__ void gemm_phase(LAS unsigned char* lds, const Params& p, const bf16_t* gA, const bf16_t* gBt, const int gM, const int gN, const int gK, const int epi, const int perm, bf16_t* const Hp, const int goff, const float coef) {
;     ...
;             PG8_LDA(At, 1, 1); PG8_STAGE(PG8_SB(1, 0), b3, voffB); PG8_STAGE(PG8_SB(1, 1), b3 + hstep, voffB); PG8_STAGE(PG8_SA(1, 0), a3, voffA);
;             PG8_WAIT_V(8); PG8_WAIT_L(0); PG8_BAR; PG8_MMA(1, 0, At, B0); PG8_MMA(1, 1, At, B1); PG8_BAR; PG8_SCHED;
;         }
;         if (wr == 0) PG8_BAR;
	s_add_i32 s30, s57, s36
	v_lshl_add_u64 v[222:223], v[222:223], 0, s[8:9]
	s_mov_b32 m0, s30
	ds_read_b128 v[190:193], v176 offset:49152
	ds_read_b128 v[194:197], v176 offset:50176
	ds_read_b128 v[198:201], v176 offset:51200
	ds_read_b128 v[202:205], v176 offset:52224
	ds_read_b128 v[206:209], v176 offset:53248
	ds_read_b128 v[210:213], v176 offset:54272
	ds_read_b128 v[214:217], v176 offset:55296
	ds_read_b128 v[218:221], v176 offset:56320
	global_load_lds_dwordx4 v[222:223], off
	s_add_i32 m0, s30, 0x2000
	s_add_u32 s28, s28, 0x80080
	v_lshl_add_u64 v[222:223], v[224:225], 0, s[8:9]
	s_addc_u32 s29, s29, 0
	s_add_i32 s30, s58, s36
	global_load_lds_dwordx4 v[222:223], off
	v_lshl_add_u64 v[222:223], s[28:29], 0, v[138:139]
	s_mov_b32 m0, s30
	s_nop 0
	global_load_lds_dwordx4 v[222:223], off
	v_lshl_add_u64 v[222:223], s[28:29], 0, v[144:145]
	s_add_i32 m0, s30, 0x2000
	s_nop 0
	global_load_lds_dwordx4 v[222:223], off
	v_lshl_add_u64 v[222:223], v[226:227], 0, s[8:9]
	s_mov_b32 m0, s44
	s_nop 0
	global_load_lds_dwordx4 v[222:223], off
	v_lshl_add_u64 v[222:223], v[228:229], 0, s[8:9]
	s_mov_b32 m0, s45
	s_nop 0
	global_load_lds_dwordx4 v[222:223], off
	s_waitcnt vmcnt(8)
	s_waitcnt lgkmcnt(0)
	s_barrier
	s_waitcnt lgkmcnt(0)
	v_mfma_f32_16x16x32_bf16 v[92:95], v[128:131], v[190:193], v[92:95]
	v_mfma_f32_16x16x32_bf16 v[88:91], v[152:155], v[190:193], v[88:91]
	v_mfma_f32_16x16x32_bf16 v[84:87], v[128:131], v[198:201], v[84:87]
	v_mfma_f32_16x16x32_bf16 v[80:83], v[152:155], v[198:201], v[80:83]
	v_mfma_f32_16x16x32_bf16 v[76:79], v[128:131], v[206:209], v[76:79]
	v_mfma_f32_16x16x32_bf16 v[72:75], v[152:155], v[206:209], v[72:75]
	v_mfma_f32_16x16x32_bf16 v[60:63], v[128:131], v[214:217], v[60:63]
	v_mfma_f32_16x16x32_bf16 v[56:59], v[152:155], v[214:217], v[56:59]
	v_mfma_f32_16x16x32_bf16 v[92:95], v[132:135], v[194:197], v[92:95]
	v_mfma_f32_16x16x32_bf16 v[88:91], v[156:159], v[194:197], v[88:91]
	v_mfma_f32_16x16x32_bf16 v[84:87], v[132:135], v[202:205], v[84:87]
	v_mfma_f32_16x16x32_bf16 v[80:83], v[156:159], v[202:205], v[80:83]
	v_mfma_f32_16x16x32_bf16 v[76:79], v[132:135], v[210:213], v[76:79]
	v_mfma_f32_16x16x32_bf16 v[72:75], v[156:159], v[210:213], v[72:75]
	v_mfma_f32_16x16x32_bf16 v[60:63], v[132:135], v[218:221], v[60:63]
	v_mfma_f32_16x16x32_bf16 v[56:59], v[156:159], v[218:221], v[56:59]
	v_mfma_f32_16x16x32_bf16 v[28:31], v[160:163], v[190:193], v[28:31]
	v_mfma_f32_16x16x32_bf16 v[24:27], v[182:185], v[190:193], v[24:27]
	v_mfma_f32_16x16x32_bf16 v[20:23], v[160:163], v[198:201], v[20:23]
	v_mfma_f32_16x16x32_bf16 v[16:19], v[182:185], v[198:201], v[16:19]
	v_mfma_f32_16x16x32_bf16 v[12:15], v[160:163], v[206:209], v[12:15]
	v_mfma_f32_16x16x32_bf16 v[8:11], v[182:185], v[206:209], v[8:11]
	v_mfma_f32_16x16x32_bf16 v[4:7], v[160:163], v[214:217], v[4:7]
	v_mfma_f32_16x16x32_bf16 v[0:3], v[182:185], v[214:217], v[0:3]
	v_mfma_f32_16x16x32_bf16 v[28:31], v[178:181], v[194:197], v[28:31]
	v_mfma_f32_16x16x32_bf16 v[24:27], v[186:189], v[194:197], v[24:27]
	v_mfma_f32_16x16x32_bf16 v[20:23], v[178:181], v[202:205], v[20:23]
	v_mfma_f32_16x16x32_bf16 v[16:19], v[186:189], v[202:205], v[16:19]
	v_mfma_f32_16x16x32_bf16 v[12:15], v[178:181], v[210:213], v[12:15]
	v_mfma_f32_16x16x32_bf16 v[8:11], v[186:189], v[210:213], v[8:11]
	v_mfma_f32_16x16x32_bf16 v[4:7], v[178:181], v[218:221], v[4:7]
	v_mfma_f32_16x16x32_bf16 v[0:3], v[186:189], v[218:221], v[0:3]
	s_barrier
	s_add_u32 s26, s26, 0x100
	s_addc_u32 s27, s27, 0
	s_add_u32 s54, s54, 0x100
	s_addc_u32 s55, s55, 0
	s_cmp_ge_u32 s56, s52
	s_mov_b32 s30, s56
	s_cbranch_scc0 .LBB0_1593
	s_and_b64 vcc, exec, s[10:11]
	s_cbranch_vccz .LBB0_1596
	s_barrier

; #define PG8_STAGE(bufoff, gbase, voff) do { _Pragma("unroll") for (int _i = 0; _i < 2; ++_i) \
;         __builtin_amdgcn_global_load_lds((const unsigned*)((const char*)(gbase) + (voff)[_i]), (LAS unsigned*)(lds + (bufoff) + ldsw + _i * 8192), 16, 0, 0); } while (0)
; #define PG8_LDA(dst, b, h) do { _Pragma("unroll") for (int m = 0; m < 4; ++m) _Pragma("unroll") for (int k = 0; k < 2; ++k) dst[m][k] = *(const LAS bf16x8*)(lds + PG8_SA(b, h) + aoff + m * 2048 + k * 1024); } while (0)
; #define PG8_LDB(dst, b, h) do { _Pragma("unroll") for (int n = 0; n < 2; ++n) _Pragma("unroll") for (int k = 0; k < 2; ++k) dst[n][k] = *(const LAS bf16x8*)(lds + PG8_SB(b, h) + boff + n * 2048 + k * 1024); } while (0)
; #define PG8_MMA(ai, bj, At, Bt) do { __builtin_amdgcn_s_setprio(1); _Pragma("unroll") for (int m = 0; m < 4; ++m) _Pragma("unroll") for (int n = 0; n < 2; ++n) _Pragma("unroll") for (int k = 0; k < 2; ++k) \
;         acc[ai][bj][m][n] = __builtin_amdgcn_mfma_f32_16x16x32_bf16(Bt[n][k], At[m][k], acc[ai][bj][m][n], 0, 0, 0); __builtin_amdgcn_s_setprio(0); } while (0)
; #define PG8_WAIT_V(n) asm volatile("s_waitcnt vmcnt(" #n ")" ::: "memory")
; #define PG8_WAIT_L(n) asm volatile("s_waitcnt lgkmcnt(" #n ")" ::: "memory")
; #define PG8_BAR __builtin_amdgcn_s_barrier()
; #define PG8_SCHED __builtin_amdgcn_sched_barrier(0)
; __device__ __forceinline__ void gemm_phase(LAS unsigned char* lds, const Params& p, const bf16_t* gA, const bf16_t* gBt, const int gM, const int gN, const int gK, const int epi, const int perm, bf16_t* const Hp, const int goff, const float coef) {
;     ...
;             const bool last = (t == nt - 2);
;             const char* a1 = cA + (size_t)(t + 1) * kstep;
;             const char* a2 = last ? nA : cA + (size_t)(t + 2) * kstep; const char* b2 = last ? nB : cB + (size_t)(t + 2) * kstep;
;             const char* a3 = a2 + kstep; const char* b3 = b2 + kstep;
;             PG8_LDB(B0, 0, 0); PG8_LDB(B1, 0, 1); PG8_SCHED; PG8_LDA(At, 0, 0); PG8_STAGE(PG8_SA(1, 1), a1 + hstep, voffA);
;             PG8_WAIT_V(8); PG8_WAIT_L(0); PG8_BAR; PG8_MMA(0, 0, At, B0); PG8_MMA(0, 1, At, B1); PG8_BAR; PG8_SCHED;
;             PG8_LDA(At, 0, 1); PG8_STAGE(PG8_SB(0, 0), b2, voffB); PG8_STAGE(PG8_SB(0, 1), b2 + hstep, voffB); PG8_STAGE(PG8_SA(0, 0), a2, voffA);
.LBB0_1737:
	ds_read_b128 v[160:163], v156
	ds_read_b128 v[164:167], v156 offset:1024
	ds_read_b128 v[168:171], v156 offset:2048
	ds_read_b128 v[172:175], v156 offset:3072
	ds_read_b128 v[176:179], v157
	ds_read_b128 v[180:183], v157 offset:1024
	ds_read_b128 v[184:187], v157 offset:2048
	ds_read_b128 v[188:191], v157 offset:3072
	s_add_i32 s54, s30, 2
	s_add_u32 s28, s26, 0xfff80080
	s_addc_u32 s29, s27, -1
	s_cmp_eq_u32 s51, s30
	s_cselect_b32 s30, s48, s28
	s_cselect_b32 s31, s13, s29
	s_cselect_b32 s29, s15, s53
	s_cselect_b32 s28, s49, s52
	v_lshl_add_u64 v[144:145], s[26:27], 0, v[136:137]
	s_add_i32 m0, s23, 0xc000
	ds_read_b128 v[192:195], v158
	ds_read_b128 v[196:199], v158 offset:1024
	ds_read_b128 v[200:203], v158 offset:2048
	ds_read_b128 v[204:207], v158 offset:3072
	ds_read_b128 v[208:211], v158 offset:4096
	ds_read_b128 v[212:215], v158 offset:5120
	ds_read_b128 v[216:219], v158 offset:6144
	ds_read_b128 v[220:223], v158 offset:7168
	global_load_lds_dwordx4 v[144:145], off
	v_lshl_add_u64 v[144:145], s[26:27], 0, v[138:139]
	s_add_i32 m0, s23, 0xe000
	s_nop 0
	global_load_lds_dwordx4 v[144:145], off
	s_waitcnt vmcnt(8)
	s_waitcnt lgkmcnt(0)
	s_barrier
	s_waitcnt lgkmcnt(0)
	v_mfma_f32_16x16x32_bf16 v[124:127], v[160:163], v[192:195], v[124:127]
	v_mfma_f32_16x16x32_bf16 v[120:123], v[168:171], v[192:195], v[120:123]
	v_mfma_f32_16x16x32_bf16 v[108:111], v[160:163], v[200:203], v[108:111]
	v_mfma_f32_16x16x32_bf16 v[104:107], v[168:171], v[200:203], v[104:107]
	v_mfma_f32_16x16x32_bf16 v[92:95], v[160:163], v[208:211], v[92:95]
	v_mfma_f32_16x16x32_bf16 v[88:91], v[168:171], v[208:211], v[88:91]
	v_mfma_f32_16x16x32_bf16 v[76:79], v[160:163], v[216:219], v[76:79]
	v_mfma_f32_16x16x32_bf16 v[72:75], v[168:171], v[216:219], v[72:75]
	v_mfma_f32_16x16x32_bf16 v[124:127], v[164:167], v[196:199], v[124:127]
	v_mfma_f32_16x16x32_bf16 v[120:123], v[172:175], v[196:199], v[120:123]
	v_mfma_f32_16x16x32_bf16 v[108:111], v[164:167], v[204:207], v[108:111]
	v_mfma_f32_16x16x32_bf16 v[104:107], v[172:175], v[204:207], v[104:107]
	v_mfma_f32_16x16x32_bf16 v[92:95], v[164:167], v[212:215], v[92:95]
	v_mfma_f32_16x16x32_bf16 v[88:91], v[172:175], v[212:215], v[88:91]
	v_mfma_f32_16x16x32_bf16 v[76:79], v[164:167], v[220:223], v[76:79]
	v_mfma_f32_16x16x32_bf16 v[72:75], v[172:175], v[220:223], v[72:75]
	v_mfma_f32_16x16x32_bf16 v[116:119], v[176:179], v[192:195], v[116:119]
	v_mfma_f32_16x16x32_bf16 v[112:115], v[184:187], v[192:195], v[112:115]
	v_mfma_f32_16x16x32_bf16 v[100:103], v[176:179], v[200:203], v[100:103]
	v_mfma_f32_16x16x32_bf16 v[96:99], v[184:187], v[200:203], v[96:99]
	v_mfma_f32_16x16x32_bf16 v[84:87], v[176:179], v[208:211], v[84:87]
	v_mfma_f32_16x16x32_bf16 v[80:83], v[184:187], v[208:211], v[80:83]
	v_mfma_f32_16x16x32_bf16 v[68:71], v[176:179], v[216:219], v[68:71]
	v_mfma_f32_16x16x32_bf16 v[64:67], v[184:187], v[216:219], v[64:67]
	v_mfma_f32_16x16x32_bf16 v[116:119], v[180:183], v[196:199], v[116:119]
	v_mfma_f32_16x16x32_bf16 v[112:115], v[188:191], v[196:199], v[112:115]
	v_mfma_f32_16x16x32_bf16 v[100:103], v[180:183], v[204:207], v[100:103]
	v_mfma_f32_16x16x32_bf16 v[96:99], v[188:191], v[204:207], v[96:99]
	v_mfma_f32_16x16x32_bf16 v[84:87], v[180:183], v[212:215], v[84:87]
	v_mfma_f32_16x16x32_bf16 v[80:83], v[188:191], v[212:215], v[80:83]
	v_mfma_f32_16x16x32_bf16 v[68:71], v[180:183], v[220:223], v[68:71]
	v_mfma_f32_16x16x32_bf16 v[64:67], v[188:191], v[220:223], v[64:67]
	s_barrier
	s_add_i32 s55, s44, s36
	v_lshl_add_u64 v[144:145], s[28:29], 0, v[130:131]
	s_mov_b32 m0, s55
	ds_read_b128 v[192:195], v158 offset:16384
	ds_read_b128 v[196:199], v158 offset:17408
	ds_read_b128 v[200:203], v158 offset:18432
	ds_read_b128 v[204:207], v158 offset:19456
	ds_read_b128 v[208:211], v158 offset:20480
	ds_read_b128 v[212:215], v158 offset:21504
	ds_read_b128 v[216:219], v158 offset:22528
	ds_read_b128 v[220:223], v158 offset:23552
	global_load_lds_dwordx4 v[144:145], off
	s_add_i32 m0, s55, 0x2000
	s_add_u32 s56, s28, 0x80000
	v_lshl_add_u64 v[224:225], s[28:29], 0, v[134:135]
	s_addc_u32 s57, s29, 0
	s_add_i32 s55, s45, s36
	global_load_lds_dwordx4 v[224:225], off
	v_lshl_add_u64 v[226:227], s[56:57], 0, v[130:131]
	s_mov_b32 m0, s55
	v_lshl_add_u64 v[228:229], s[30:31], 0, v[132:133]
	global_load_lds_dwordx4 v[226:227], off
	v_lshl_add_u64 v[226:227], s[56:57], 0, v[134:135]
	s_add_i32 m0, s55, 0x2000
	s_nop 0
	global_load_lds_dwordx4 v[226:227], off
	v_lshl_add_u64 v[226:227], s[30:31], 0, v[128:129]
	s_mov_b32 m0, s23
	s_nop 0
	global_load_lds_dwordx4 v[226:227], off
	s_mov_b32 m0, s25
	s_nop 0
	global_load_lds_dwordx4 v[228:229], off
	s_waitcnt vmcnt(8)
	s_waitcnt lgkmcnt(0)
	s_barrier
; #define PG8_STAGE(bufoff, gbase, voff) do { _Pragma("unroll") for (int _i = 0; _i < 2; ++_i) \
;         __builtin_amdgcn_global_load_lds((const unsigned*)((const char*)(gbase) + (voff)[_i]), (LAS unsigned*)(lds + (bufoff) + ldsw + _i * 8192), 16, 0, 0); } while (0)
; #define PG8_LDA(dst, b, h) do { _Pragma("unroll") for (int m = 0; m < 4; ++m) _Pragma("unroll") for (int k = 0; k < 2; ++k) dst[m][k] = *(const LAS bf16x8*)(lds + PG8_SA(b, h) + aoff + m * 2048 + k * 1024); } while (0)
; #define PG8_LDB(dst, b, h) do { _Pragma("unroll") for (int n = 0; n < 2; ++n) _Pragma("unroll") for (int k = 0; k < 2; ++k) dst[n][k] = *(const LAS bf16x8*)(lds + PG8_SB(b, h) + boff + n * 2048 + k * 1024); } while (0)
; #define PG8_MMA(ai, bj, At, Bt) do { __builtin_amdgcn_s_setprio(1); _Pragma("unroll") for (int m = 0; m < 4; ++m) _Pragma("unroll") for (int n = 0; n < 2; ++n) _Pragma("unroll") for (int k = 0; k < 2; ++k) \
;         acc[ai][bj][m][n] = __builtin_amdgcn_mfma_f32_16x16x32_bf16(Bt[n][k], At[m][k], acc[ai][bj][m][n], 0, 0, 0); __builtin_amdgcn_s_setprio(0); } while (0)
; #define PG8_WAIT_V(n) asm volatile("s_waitcnt vmcnt(" #n ")" ::: "memory")
; #define PG8_WAIT_L(n) asm volatile("s_waitcnt lgkmcnt(" #n ")" ::: "memory")
; #define PG8_BAR __builtin_amdgcn_s_barrier()
; #define PG8_SCHED __builtin_amdgcn_sched_barrier(0)
; __device__ __forceinline__ void gemm_phase(LAS unsigned char* lds, const Params& p, const bf16_t* gA, const bf16_t* gBt, const int gM, const int gN, const int gK, const int epi, const int perm, bf16_t* const Hp, const int goff, const float coef) {
;     ...
;             PG8_WAIT_V(8); PG8_WAIT_L(0); PG8_BAR; PG8_MMA(1, 0, At, B0); PG8_MMA(1, 1, At, B1); PG8_BAR; PG8_SCHED;
;             PG8_LDB(B0, 1, 0); PG8_LDB(B1, 1, 1); PG8_SCHED; PG8_LDA(At, 1, 0); PG8_STAGE(PG8_SA(0, 1), a2 + hstep, voffA);
;             PG8_WAIT_V(8); PG8_WAIT_L(0); PG8_BAR; PG8_MMA(0, 0, At, B0); PG8_MMA(0, 1, At, B1); PG8_BAR; PG8_SCHED;
	s_waitcnt lgkmcnt(0)
	v_mfma_f32_16x16x32_bf16 v[60:63], v[160:163], v[192:195], v[60:63]
	v_mfma_f32_16x16x32_bf16 v[56:59], v[168:171], v[192:195], v[56:59]
	v_mfma_f32_16x16x32_bf16 v[44:47], v[160:163], v[200:203], v[44:47]
	v_mfma_f32_16x16x32_bf16 v[40:43], v[168:171], v[200:203], v[40:43]
	v_mfma_f32_16x16x32_bf16 v[28:31], v[160:163], v[208:211], v[28:31]
	v_mfma_f32_16x16x32_bf16 v[24:27], v[168:171], v[208:211], v[24:27]
	v_mfma_f32_16x16x32_bf16 v[12:15], v[160:163], v[216:219], v[12:15]
	v_mfma_f32_16x16x32_bf16 v[8:11], v[168:171], v[216:219], v[8:11]
	v_mfma_f32_16x16x32_bf16 v[60:63], v[164:167], v[196:199], v[60:63]
	v_mfma_f32_16x16x32_bf16 v[56:59], v[172:175], v[196:199], v[56:59]
	v_mfma_f32_16x16x32_bf16 v[44:47], v[164:167], v[204:207], v[44:47]
	v_mfma_f32_16x16x32_bf16 v[40:43], v[172:175], v[204:207], v[40:43]
	v_mfma_f32_16x16x32_bf16 v[28:31], v[164:167], v[212:215], v[28:31]
	v_mfma_f32_16x16x32_bf16 v[24:27], v[172:175], v[212:215], v[24:27]
	v_mfma_f32_16x16x32_bf16 v[12:15], v[164:167], v[220:223], v[12:15]
	v_mfma_f32_16x16x32_bf16 v[8:11], v[172:175], v[220:223], v[8:11]
	v_mfma_f32_16x16x32_bf16 v[52:55], v[176:179], v[192:195], v[52:55]
	v_mfma_f32_16x16x32_bf16 v[48:51], v[184:187], v[192:195], v[48:51]
	v_mfma_f32_16x16x32_bf16 v[36:39], v[176:179], v[200:203], v[36:39]
	v_mfma_f32_16x16x32_bf16 v[32:35], v[184:187], v[200:203], v[32:35]
	v_mfma_f32_16x16x32_bf16 v[20:23], v[176:179], v[208:211], v[20:23]
	v_mfma_f32_16x16x32_bf16 v[16:19], v[184:187], v[208:211], v[16:19]
	v_mfma_f32_16x16x32_bf16 v[4:7], v[176:179], v[216:219], v[4:7]
	v_mfma_f32_16x16x32_bf16 v[0:3], v[184:187], v[216:219], v[0:3]
	v_mfma_f32_16x16x32_bf16 v[52:55], v[180:183], v[196:199], v[52:55]
	v_mfma_f32_16x16x32_bf16 v[48:51], v[188:191], v[196:199], v[48:51]
	v_mfma_f32_16x16x32_bf16 v[36:39], v[180:183], v[204:207], v[36:39]
	v_mfma_f32_16x16x32_bf16 v[32:35], v[188:191], v[204:207], v[32:35]
	v_mfma_f32_16x16x32_bf16 v[20:23], v[180:183], v[212:215], v[20:23]
	v_mfma_f32_16x16x32_bf16 v[16:19], v[188:191], v[212:215], v[16:19]
	v_mfma_f32_16x16x32_bf16 v[4:7], v[180:183], v[220:223], v[4:7]
	v_mfma_f32_16x16x32_bf16 v[0:3], v[188:191], v[220:223], v[0:3]
	s_barrier
	s_add_i32 s55, 0, 0x18000
	v_add_u32_e32 v141, s55, v147
	s_add_i32 s56, 0, 0x1c000
	ds_read_b128 v[160:163], v141
	ds_read_b128 v[164:167], v141 offset:1024
	ds_read_b128 v[168:171], v141 offset:2048
	ds_read_b128 v[172:175], v141 offset:3072
	v_add_u32_e32 v141, s56, v147
	ds_read_b128 v[176:179], v141
	ds_read_b128 v[180:183], v141 offset:1024
	ds_read_b128 v[184:187], v141 offset:2048
	ds_read_b128 v[188:191], v141 offset:3072
	s_add_u32 s30, s30, 0x80000
	s_addc_u32 s31, s31, 0
	s_mov_b32 m0, s37
	v_lshl_add_u64 v[230:231], s[30:31], 0, v[128:129]
	ds_read_b128 v[192:195], v158 offset:32768
	ds_read_b128 v[196:199], v158 offset:33792
	ds_read_b128 v[200:203], v158 offset:34816
	ds_read_b128 v[204:207], v158 offset:35840
	ds_read_b128 v[208:211], v158 offset:36864
	ds_read_b128 v[212:215], v158 offset:37888
	ds_read_b128 v[216:219], v158 offset:38912
	ds_read_b128 v[220:223], v158 offset:39936
	global_load_lds_dwordx4 v[230:231], off
	v_lshl_add_u64 v[230:231], s[30:31], 0, v[132:133]
	s_mov_b32 m0, s38
	s_nop 0
	global_load_lds_dwordx4 v[230:231], off
	s_waitcnt vmcnt(8)
	s_waitcnt lgkmcnt(0)
	s_barrier
	s_waitcnt lgkmcnt(0)
	v_mfma_f32_16x16x32_bf16 v[124:127], v[160:163], v[192:195], v[124:127]
	v_mfma_f32_16x16x32_bf16 v[120:123], v[168:171], v[192:195], v[120:123]
	v_mfma_f32_16x16x32_bf16 v[108:111], v[160:163], v[200:203], v[108:111]
	v_mfma_f32_16x16x32_bf16 v[104:107], v[168:171], v[200:203], v[104:107]
	v_mfma_f32_16x16x32_bf16 v[92:95], v[160:163], v[208:211], v[92:95]
	v_mfma_f32_16x16x32_bf16 v[88:91], v[168:171], v[208:211], v[88:91]
	v_mfma_f32_16x16x32_bf16 v[76:79], v[160:163], v[216:219], v[76:79]
	v_mfma_f32_16x16x32_bf16 v[72:75], v[168:171], v[216:219], v[72:75]
	v_mfma_f32_16x16x32_bf16 v[124:127], v[164:167], v[196:199], v[124:127]
	v_mfma_f32_16x16x32_bf16 v[120:123], v[172:175], v[196:199], v[120:123]
	v_mfma_f32_16x16x32_bf16 v[108:111], v[164:167], v[204:207], v[108:111]
	v_mfma_f32_16x16x32_bf16 v[104:107], v[172:175], v[204:207], v[104:107]
	v_mfma_f32_16x16x32_bf16 v[92:95], v[164:167], v[212:215], v[92:95]
	v_mfma_f32_16x16x32_bf16 v[88:91], v[172:175], v[212:215], v[88:91]
	v_mfma_f32_16x16x32_bf16 v[76:79], v[164:167], v[220:223], v[76:79]
	v_mfma_f32_16x16x32_bf16 v[72:75], v[172:175], v[220:223], v[72:75]
	v_mfma_f32_16x16x32_bf16 v[116:119], v[176:179], v[192:195], v[116:119]
	v_mfma_f32_16x16x32_bf16 v[112:115], v[184:187], v[192:195], v[112:115]
	v_mfma_f32_16x16x32_bf16 v[100:103], v[176:179], v[200:203], v[100:103]
	v_mfma_f32_16x16x32_bf16 v[96:99], v[184:187], v[200:203], v[96:99]
	v_mfma_f32_16x16x32_bf16 v[84:87], v[176:179], v[208:211], v[84:87]
	v_mfma_f32_16x16x32_bf16 v[80:83], v[184:187], v[208:211], v[80:83]
	v_mfma_f32_16x16x32_bf16 v[68:71], v[176:179], v[216:219], v[68:71]
	v_mfma_f32_16x16x32_bf16 v[64:67], v[184:187], v[216:219], v[64:67]
	v_mfma_f32_16x16x32_bf16 v[116:119], v[180:183], v[196:199], v[116:119]
	v_mfma_f32_16x16x32_bf16 v[112:115], v[188:191], v[196:199], v[112:115]
	v_mfma_f32_16x16x32_bf16 v[100:103], v[180:183], v[204:207], v[100:103]
	v_mfma_f32_16x16x32_bf16 v[96:99], v[188:191], v[204:207], v[96:99]
	v_mfma_f32_16x16x32_bf16 v[84:87], v[180:183], v[212:215], v[84:87]
	v_mfma_f32_16x16x32_bf16 v[80:83], v[188:191], v[212:215], v[80:83]
	v_mfma_f32_16x16x32_bf16 v[68:71], v[180:183], v[220:223], v[68:71]
	v_mfma_f32_16x16x32_bf16 v[64:67], v[188:191], v[220:223], v[64:67]
	s_barrier
; #define PG8_STAGE(bufoff, gbase, voff) do { _Pragma("unroll") for (int _i = 0; _i < 2; ++_i) \
;         __builtin_amdgcn_global_load_lds((const unsigned*)((const char*)(gbase) + (voff)[_i]), (LAS unsigned*)(lds + (bufoff) + ldsw + _i * 8192), 16, 0, 0); } while (0)
; #define PG8_LDA(dst, b, h) do { _Pragma("unroll") for (int m = 0; m < 4; ++m) _Pragma("unroll") for (int k = 0; k < 2; ++k) dst[m][k] = *(const LAS bf16x8*)(lds + PG8_SA(b, h) + aoff + m * 2048 + k * 1024); } while (0)
; #define PG8_MMA(ai, bj, At, Bt) do { __builtin_amdgcn_s_setprio(1); _Pragma("unroll") for (int m = 0; m < 4; ++m) _Pragma("unroll") for (int n = 0; n < 2; ++n) _Pragma("unroll") for (int k = 0; k < 2; ++k) \
;         acc[ai][bj][m][n] = __builtin_amdgcn_mfma_f32_16x16x32_bf16(Bt[n][k], At[m][k], acc[ai][bj][m][n], 0, 0, 0); __builtin_amdgcn_s_setprio(0); } while (0)
; #define PG8_WAIT_V(n) asm volatile("s_waitcnt vmcnt(" #n ")" ::: "memory")
; #define PG8_WAIT_L(n) asm volatile("s_waitcnt lgkmcnt(" #n ")" ::: "memory")
; #define PG8_BAR __builtin_amdgcn_s_barrier()
; #define PG8_SCHED __builtin_amdgcn_sched_barrier(0)
; __device__ __forceinline__ void gemm_phase(LAS unsigned char* lds, const Params& p, const bf16_t* gA, const bf16_t* gBt, const int gM, const int gN, const int gK, const int epi, const int perm, bf16_t* const Hp, const int goff, const float coef) {
;     ...
;             PG8_LDA(At, 1, 1); PG8_STAGE(PG8_SB(1, 0), b3, voffB); PG8_STAGE(PG8_SB(1, 1), b3 + hstep, voffB); PG8_STAGE(PG8_SA(1, 0), a3, voffA);
;             PG8_WAIT_V(8); PG8_WAIT_L(0); PG8_BAR; PG8_MMA(1, 0, At, B0); PG8_MMA(1, 1, At, B1); PG8_BAR; PG8_SCHED;
;         }
;         if (wr == 0) PG8_BAR;
	s_add_i32 s30, s55, s36
	v_lshl_add_u64 v[144:145], v[144:145], 0, s[8:9]
	s_mov_b32 m0, s30
	ds_read_b128 v[192:195], v158 offset:49152
	ds_read_b128 v[196:199], v158 offset:50176
	ds_read_b128 v[200:203], v158 offset:51200
	ds_read_b128 v[204:207], v158 offset:52224
	ds_read_b128 v[208:211], v158 offset:53248
	ds_read_b128 v[212:215], v158 offset:54272
	ds_read_b128 v[216:219], v158 offset:55296
	ds_read_b128 v[220:223], v158 offset:56320
	global_load_lds_dwordx4 v[144:145], off
	s_add_i32 m0, s30, 0x2000
	s_add_u32 s28, s28, 0x80080
	v_lshl_add_u64 v[144:145], v[224:225], 0, s[8:9]
	s_addc_u32 s29, s29, 0
	s_add_i32 s30, s56, s36
	global_load_lds_dwordx4 v[144:145], off
	v_lshl_add_u64 v[144:145], s[28:29], 0, v[130:131]
	s_mov_b32 m0, s30
	s_nop 0
	global_load_lds_dwordx4 v[144:145], off
	v_lshl_add_u64 v[144:145], s[28:29], 0, v[134:135]
	s_add_i32 m0, s30, 0x2000
	s_nop 0
	global_load_lds_dwordx4 v[144:145], off
	v_lshl_add_u64 v[144:145], v[226:227], 0, s[8:9]
	s_mov_b32 m0, s40
	s_nop 0
	global_load_lds_dwordx4 v[144:145], off
	v_lshl_add_u64 v[144:145], v[228:229], 0, s[8:9]
	s_mov_b32 m0, s41
	s_nop 0
	global_load_lds_dwordx4 v[144:145], off
	s_waitcnt vmcnt(8)
	s_waitcnt lgkmcnt(0)
	s_barrier
	s_waitcnt lgkmcnt(0)
	v_mfma_f32_16x16x32_bf16 v[60:63], v[160:163], v[192:195], v[60:63]
	v_mfma_f32_16x16x32_bf16 v[56:59], v[168:171], v[192:195], v[56:59]
	v_mfma_f32_16x16x32_bf16 v[44:47], v[160:163], v[200:203], v[44:47]
	v_mfma_f32_16x16x32_bf16 v[40:43], v[168:171], v[200:203], v[40:43]
	v_mfma_f32_16x16x32_bf16 v[28:31], v[160:163], v[208:211], v[28:31]
	v_mfma_f32_16x16x32_bf16 v[24:27], v[168:171], v[208:211], v[24:27]
	v_mfma_f32_16x16x32_bf16 v[12:15], v[160:163], v[216:219], v[12:15]
	v_mfma_f32_16x16x32_bf16 v[8:11], v[168:171], v[216:219], v[8:11]
	v_mfma_f32_16x16x32_bf16 v[60:63], v[164:167], v[196:199], v[60:63]
	v_mfma_f32_16x16x32_bf16 v[56:59], v[172:175], v[196:199], v[56:59]
	v_mfma_f32_16x16x32_bf16 v[44:47], v[164:167], v[204:207], v[44:47]
	v_mfma_f32_16x16x32_bf16 v[40:43], v[172:175], v[204:207], v[40:43]
	v_mfma_f32_16x16x32_bf16 v[28:31], v[164:167], v[212:215], v[28:31]
	v_mfma_f32_16x16x32_bf16 v[24:27], v[172:175], v[212:215], v[24:27]
	v_mfma_f32_16x16x32_bf16 v[12:15], v[164:167], v[220:223], v[12:15]
	v_mfma_f32_16x16x32_bf16 v[8:11], v[172:175], v[220:223], v[8:11]
	v_mfma_f32_16x16x32_bf16 v[52:55], v[176:179], v[192:195], v[52:55]
	v_mfma_f32_16x16x32_bf16 v[48:51], v[184:187], v[192:195], v[48:51]
	v_mfma_f32_16x16x32_bf16 v[36:39], v[176:179], v[200:203], v[36:39]
	v_mfma_f32_16x16x32_bf16 v[32:35], v[184:187], v[200:203], v[32:35]
	v_mfma_f32_16x16x32_bf16 v[20:23], v[176:179], v[208:211], v[20:23]
	v_mfma_f32_16x16x32_bf16 v[16:19], v[184:187], v[208:211], v[16:19]
	v_mfma_f32_16x16x32_bf16 v[4:7], v[176:179], v[216:219], v[4:7]
	v_mfma_f32_16x16x32_bf16 v[0:3], v[184:187], v[216:219], v[0:3]
	v_mfma_f32_16x16x32_bf16 v[52:55], v[180:183], v[196:199], v[52:55]
	v_mfma_f32_16x16x32_bf16 v[48:51], v[188:191], v[196:199], v[48:51]
	v_mfma_f32_16x16x32_bf16 v[36:39], v[180:183], v[204:207], v[36:39]
	v_mfma_f32_16x16x32_bf16 v[32:35], v[188:191], v[204:207], v[32:35]
	v_mfma_f32_16x16x32_bf16 v[20:23], v[180:183], v[212:215], v[20:23]
	v_mfma_f32_16x16x32_bf16 v[16:19], v[188:191], v[212:215], v[16:19]
	v_mfma_f32_16x16x32_bf16 v[4:7], v[180:183], v[220:223], v[4:7]
	v_mfma_f32_16x16x32_bf16 v[0:3], v[188:191], v[220:223], v[0:3]
	s_barrier
	s_add_u32 s26, s26, 0x100
	s_addc_u32 s27, s27, 0
	s_add_u32 s52, s52, 0x100
	s_addc_u32 s53, s53, 0
	s_cmp_ge_u32 s54, s50
	s_mov_b32 s30, s54
	s_cbranch_scc0 .LBB0_1737
	s_and_b64 vcc, exec, s[10:11]
	s_cbranch_vccz .LBB0_1740
	s_barrier

; #define PG8_STAGE(bufoff, gbase, voff) do { _Pragma("unroll") for (int _i = 0; _i < 2; ++_i) \
;         __builtin_amdgcn_global_load_lds((const unsigned*)((const char*)(gbase) + (voff)[_i]), (LAS unsigned*)(lds + (bufoff) + ldsw + _i * 8192), 16, 0, 0); } while (0)
; #define PG8_LDA(dst, b, h) do { _Pragma("unroll") for (int m = 0; m < 4; ++m) _Pragma("unroll") for (int k = 0; k < 2; ++k) dst[m][k] = *(const LAS bf16x8*)(lds + PG8_SA(b, h) + aoff + m * 2048 + k * 1024); } while (0)
; #define PG8_LDB(dst, b, h) do { _Pragma("unroll") for (int n = 0; n < 2; ++n) _Pragma("unroll") for (int k = 0; k < 2; ++k) dst[n][k] = *(const LAS bf16x8*)(lds + PG8_SB(b, h) + boff + n * 2048 + k * 1024); } while (0)
; #define PG8_MMA(ai, bj, At, Bt) do { __builtin_amdgcn_s_setprio(1); _Pragma("unroll") for (int m = 0; m < 4; ++m) _Pragma("unroll") for (int n = 0; n < 2; ++n) _Pragma("unroll") for (int k = 0; k < 2; ++k) \
;         acc[ai][bj][m][n] = __builtin_amdgcn_mfma_f32_16x16x32_bf16(Bt[n][k], At[m][k], acc[ai][bj][m][n], 0, 0, 0); __builtin_amdgcn_s_setprio(0); } while (0)
; #define PG8_WAIT_V(n) asm volatile("s_waitcnt vmcnt(" #n ")" ::: "memory")
; #define PG8_WAIT_L(n) asm volatile("s_waitcnt lgkmcnt(" #n ")" ::: "memory")
; #define PG8_BAR __builtin_amdgcn_s_barrier()
; #define PG8_SCHED __builtin_amdgcn_sched_barrier(0)
; __device__ __forceinline__ void gemm_phase(LAS unsigned char* lds, const Params& p, const bf16_t* gA, const bf16_t* gBt, const int gM, const int gN, const int gK, const int epi, const int perm, bf16_t* const Hp, const int goff, const float coef) {
;     ...
;             const bool last = (t == nt - 2);
;             const char* a1 = cA + (size_t)(t + 1) * kstep;
;             const char* a2 = last ? nA : cA + (size_t)(t + 2) * kstep; const char* b2 = last ? nB : cB + (size_t)(t + 2) * kstep;
;             const char* a3 = a2 + kstep; const char* b3 = b2 + kstep;
;             PG8_LDB(B0, 0, 0); PG8_LDB(B1, 0, 1); PG8_SCHED; PG8_LDA(At, 0, 0); PG8_STAGE(PG8_SA(1, 1), a1 + hstep, voffA);
;             PG8_WAIT_V(8); PG8_WAIT_L(0); PG8_BAR; PG8_MMA(0, 0, At, B0); PG8_MMA(0, 1, At, B1); PG8_BAR; PG8_SCHED;
;             PG8_LDA(At, 0, 1); PG8_STAGE(PG8_SB(0, 0), b2, voffB); PG8_STAGE(PG8_SB(0, 1), b2 + hstep, voffB); PG8_STAGE(PG8_SA(0, 0), a2, voffA);
.LBB0_1827:
	ds_read_b128 v[144:147], v166
	ds_read_b128 v[148:151], v166 offset:1024
	ds_read_b128 v[152:155], v166 offset:2048
	ds_read_b128 v[170:173], v166 offset:3072
	ds_read_b128 v[174:177], v167
	ds_read_b128 v[178:181], v167 offset:1024
	ds_read_b128 v[182:185], v167 offset:2048
	ds_read_b128 v[186:189], v167 offset:3072
	s_add_i32 s54, s20, 2
	s_add_u32 s21, s18, 0xffea0080
	s_addc_u32 s22, s19, -1
	s_cmp_eq_u32 s51, s20
	s_cselect_b32 s20, s16, s52
	s_cselect_b32 s23, s15, s22
	s_cselect_b32 s22, s14, s21
	s_cselect_b32 s21, s17, s53
	v_lshl_add_u64 v[222:223], s[18:19], 0, v[136:137]
	s_add_i32 m0, s28, 0xc000
	ds_read_b128 v[190:193], v168
	ds_read_b128 v[194:197], v168 offset:1024
	ds_read_b128 v[198:201], v168 offset:2048
	ds_read_b128 v[202:205], v168 offset:3072
	ds_read_b128 v[206:209], v168 offset:4096
	ds_read_b128 v[210:213], v168 offset:5120
	ds_read_b128 v[214:217], v168 offset:6144
	ds_read_b128 v[218:221], v168 offset:7168
	global_load_lds_dwordx4 v[222:223], off
	v_lshl_add_u64 v[222:223], s[18:19], 0, v[138:139]
	s_add_i32 m0, s28, 0xe000
	s_nop 0
	global_load_lds_dwordx4 v[222:223], off
	s_waitcnt vmcnt(8)
	s_waitcnt lgkmcnt(0)
	s_barrier
	s_waitcnt lgkmcnt(0)
	v_mfma_f32_16x16x32_bf16 v[124:127], v[144:147], v[190:193], v[124:127]
	v_mfma_f32_16x16x32_bf16 v[120:123], v[152:155], v[190:193], v[120:123]
	v_mfma_f32_16x16x32_bf16 v[116:119], v[144:147], v[198:201], v[116:119]
	v_mfma_f32_16x16x32_bf16 v[112:115], v[152:155], v[198:201], v[112:115]
	v_mfma_f32_16x16x32_bf16 v[108:111], v[144:147], v[206:209], v[108:111]
	v_mfma_f32_16x16x32_bf16 v[104:107], v[152:155], v[206:209], v[104:107]
	v_mfma_f32_16x16x32_bf16 v[100:103], v[144:147], v[214:217], v[100:103]
	v_mfma_f32_16x16x32_bf16 v[96:99], v[152:155], v[214:217], v[96:99]
	v_mfma_f32_16x16x32_bf16 v[124:127], v[148:151], v[194:197], v[124:127]
	v_mfma_f32_16x16x32_bf16 v[120:123], v[170:173], v[194:197], v[120:123]
	v_mfma_f32_16x16x32_bf16 v[116:119], v[148:151], v[202:205], v[116:119]
	v_mfma_f32_16x16x32_bf16 v[112:115], v[170:173], v[202:205], v[112:115]
	v_mfma_f32_16x16x32_bf16 v[108:111], v[148:151], v[210:213], v[108:111]
	v_mfma_f32_16x16x32_bf16 v[104:107], v[170:173], v[210:213], v[104:107]
	v_mfma_f32_16x16x32_bf16 v[100:103], v[148:151], v[218:221], v[100:103]
	v_mfma_f32_16x16x32_bf16 v[96:99], v[170:173], v[218:221], v[96:99]
	v_mfma_f32_16x16x32_bf16 v[68:71], v[174:177], v[190:193], v[68:71]
	v_mfma_f32_16x16x32_bf16 v[60:63], v[182:185], v[190:193], v[60:63]
	v_mfma_f32_16x16x32_bf16 v[52:55], v[174:177], v[198:201], v[52:55]
	v_mfma_f32_16x16x32_bf16 v[48:51], v[182:185], v[198:201], v[48:51]
	v_mfma_f32_16x16x32_bf16 v[44:47], v[174:177], v[206:209], v[44:47]
	v_mfma_f32_16x16x32_bf16 v[40:43], v[182:185], v[206:209], v[40:43]
	v_mfma_f32_16x16x32_bf16 v[36:39], v[174:177], v[214:217], v[36:39]
	v_mfma_f32_16x16x32_bf16 v[32:35], v[182:185], v[214:217], v[32:35]
	v_mfma_f32_16x16x32_bf16 v[68:71], v[178:181], v[194:197], v[68:71]
	v_mfma_f32_16x16x32_bf16 v[60:63], v[186:189], v[194:197], v[60:63]
	v_mfma_f32_16x16x32_bf16 v[52:55], v[178:181], v[202:205], v[52:55]
	v_mfma_f32_16x16x32_bf16 v[48:51], v[186:189], v[202:205], v[48:51]
	v_mfma_f32_16x16x32_bf16 v[44:47], v[178:181], v[210:213], v[44:47]
	v_mfma_f32_16x16x32_bf16 v[40:43], v[186:189], v[210:213], v[40:43]
	v_mfma_f32_16x16x32_bf16 v[36:39], v[178:181], v[218:221], v[36:39]
	v_mfma_f32_16x16x32_bf16 v[32:35], v[186:189], v[218:221], v[32:35]
	s_barrier
	s_add_i32 s55, s42, s27
	v_lshl_add_u64 v[222:223], s[20:21], 0, v[130:131]
	s_mov_b32 m0, s55
	ds_read_b128 v[190:193], v168 offset:16384
	ds_read_b128 v[194:197], v168 offset:17408
	ds_read_b128 v[198:201], v168 offset:18432
	ds_read_b128 v[202:205], v168 offset:19456
	ds_read_b128 v[206:209], v168 offset:20480
	ds_read_b128 v[210:213], v168 offset:21504
	ds_read_b128 v[214:217], v168 offset:22528
	ds_read_b128 v[218:221], v168 offset:23552
	global_load_lds_dwordx4 v[222:223], off
	s_add_i32 m0, s55, 0x2000
	s_add_u32 s56, s20, 0x160000
	v_lshl_add_u64 v[224:225], s[20:21], 0, v[134:135]
	s_addc_u32 s57, s21, 0
	s_add_i32 s55, s43, s27
	global_load_lds_dwordx4 v[224:225], off
	v_lshl_add_u64 v[226:227], s[56:57], 0, v[130:131]
	s_mov_b32 m0, s55
	v_lshl_add_u64 v[228:229], s[22:23], 0, v[132:133]
	global_load_lds_dwordx4 v[226:227], off
	v_lshl_add_u64 v[226:227], s[56:57], 0, v[134:135]
	s_add_i32 m0, s55, 0x2000
	s_nop 0
	global_load_lds_dwordx4 v[226:227], off
	v_lshl_add_u64 v[226:227], s[22:23], 0, v[128:129]
	s_mov_b32 m0, s28
	s_nop 0
	global_load_lds_dwordx4 v[226:227], off
	s_mov_b32 m0, s29
	s_nop 0
	global_load_lds_dwordx4 v[228:229], off
	s_waitcnt vmcnt(8)
	s_waitcnt lgkmcnt(0)
	s_barrier
; #define PG8_STAGE(bufoff, gbase, voff) do { _Pragma("unroll") for (int _i = 0; _i < 2; ++_i) \
;         __builtin_amdgcn_global_load_lds((const unsigned*)((const char*)(gbase) + (voff)[_i]), (LAS unsigned*)(lds + (bufoff) + ldsw + _i * 8192), 16, 0, 0); } while (0)
; #define PG8_LDA(dst, b, h) do { _Pragma("unroll") for (int m = 0; m < 4; ++m) _Pragma("unroll") for (int k = 0; k < 2; ++k) dst[m][k] = *(const LAS bf16x8*)(lds + PG8_SA(b, h) + aoff + m * 2048 + k * 1024); } while (0)
; #define PG8_LDB(dst, b, h) do { _Pragma("unroll") for (int n = 0; n < 2; ++n) _Pragma("unroll") for (int k = 0; k < 2; ++k) dst[n][k] = *(const LAS bf16x8*)(lds + PG8_SB(b, h) + boff + n * 2048 + k * 1024); } while (0)
; #define PG8_MMA(ai, bj, At, Bt) do { __builtin_amdgcn_s_setprio(1); _Pragma("unroll") for (int m = 0; m < 4; ++m) _Pragma("unroll") for (int n = 0; n < 2; ++n) _Pragma("unroll") for (int k = 0; k < 2; ++k) \
;         acc[ai][bj][m][n] = __builtin_amdgcn_mfma_f32_16x16x32_bf16(Bt[n][k], At[m][k], acc[ai][bj][m][n], 0, 0, 0); __builtin_amdgcn_s_setprio(0); } while (0)
; #define PG8_WAIT_V(n) asm volatile("s_waitcnt vmcnt(" #n ")" ::: "memory")
; #define PG8_WAIT_L(n) asm volatile("s_waitcnt lgkmcnt(" #n ")" ::: "memory")
; #define PG8_BAR __builtin_amdgcn_s_barrier()
; #define PG8_SCHED __builtin_amdgcn_sched_barrier(0)
; __device__ __forceinline__ void gemm_phase(LAS unsigned char* lds, const Params& p, const bf16_t* gA, const bf16_t* gBt, const int gM, const int gN, const int gK, const int epi, const int perm, bf16_t* const Hp, const int goff, const float coef) {
;     ...
;             PG8_WAIT_V(8); PG8_WAIT_L(0); PG8_BAR; PG8_MMA(1, 0, At, B0); PG8_MMA(1, 1, At, B1); PG8_BAR; PG8_SCHED;
;             PG8_LDB(B0, 1, 0); PG8_LDB(B1, 1, 1); PG8_SCHED; PG8_LDA(At, 1, 0); PG8_STAGE(PG8_SA(0, 1), a2 + hstep, voffA);
;             PG8_WAIT_V(8); PG8_WAIT_L(0); PG8_BAR; PG8_MMA(0, 0, At, B0); PG8_MMA(0, 1, At, B1); PG8_BAR; PG8_SCHED;
	s_waitcnt lgkmcnt(0)
	v_mfma_f32_16x16x32_bf16 v[92:95], v[144:147], v[190:193], v[92:95]
	v_mfma_f32_16x16x32_bf16 v[88:91], v[152:155], v[190:193], v[88:91]
	v_mfma_f32_16x16x32_bf16 v[84:87], v[144:147], v[198:201], v[84:87]
	v_mfma_f32_16x16x32_bf16 v[80:83], v[152:155], v[198:201], v[80:83]
	v_mfma_f32_16x16x32_bf16 v[76:79], v[144:147], v[206:209], v[76:79]
	v_mfma_f32_16x16x32_bf16 v[72:75], v[152:155], v[206:209], v[72:75]
	v_mfma_f32_16x16x32_bf16 v[64:67], v[144:147], v[214:217], v[64:67]
	v_mfma_f32_16x16x32_bf16 v[56:59], v[152:155], v[214:217], v[56:59]
	v_mfma_f32_16x16x32_bf16 v[92:95], v[148:151], v[194:197], v[92:95]
	v_mfma_f32_16x16x32_bf16 v[88:91], v[170:173], v[194:197], v[88:91]
	v_mfma_f32_16x16x32_bf16 v[84:87], v[148:151], v[202:205], v[84:87]
	v_mfma_f32_16x16x32_bf16 v[80:83], v[170:173], v[202:205], v[80:83]
	v_mfma_f32_16x16x32_bf16 v[76:79], v[148:151], v[210:213], v[76:79]
	v_mfma_f32_16x16x32_bf16 v[72:75], v[170:173], v[210:213], v[72:75]
	v_mfma_f32_16x16x32_bf16 v[64:67], v[148:151], v[218:221], v[64:67]
	v_mfma_f32_16x16x32_bf16 v[56:59], v[170:173], v[218:221], v[56:59]
	v_mfma_f32_16x16x32_bf16 v[28:31], v[174:177], v[190:193], v[28:31]
	v_mfma_f32_16x16x32_bf16 v[24:27], v[182:185], v[190:193], v[24:27]
	v_mfma_f32_16x16x32_bf16 v[20:23], v[174:177], v[198:201], v[20:23]
	v_mfma_f32_16x16x32_bf16 v[16:19], v[182:185], v[198:201], v[16:19]
	v_mfma_f32_16x16x32_bf16 v[12:15], v[174:177], v[206:209], v[12:15]
	v_mfma_f32_16x16x32_bf16 v[8:11], v[182:185], v[206:209], v[8:11]
	v_mfma_f32_16x16x32_bf16 v[4:7], v[174:177], v[214:217], v[4:7]
	v_mfma_f32_16x16x32_bf16 v[0:3], v[182:185], v[214:217], v[0:3]
	v_mfma_f32_16x16x32_bf16 v[28:31], v[178:181], v[194:197], v[28:31]
	v_mfma_f32_16x16x32_bf16 v[24:27], v[186:189], v[194:197], v[24:27]
	v_mfma_f32_16x16x32_bf16 v[20:23], v[178:181], v[202:205], v[20:23]
	v_mfma_f32_16x16x32_bf16 v[16:19], v[186:189], v[202:205], v[16:19]
	v_mfma_f32_16x16x32_bf16 v[12:15], v[178:181], v[210:213], v[12:15]
	v_mfma_f32_16x16x32_bf16 v[8:11], v[186:189], v[210:213], v[8:11]
	v_mfma_f32_16x16x32_bf16 v[4:7], v[178:181], v[218:221], v[4:7]
	v_mfma_f32_16x16x32_bf16 v[0:3], v[186:189], v[218:221], v[0:3]
	s_barrier
	s_add_i32 s55, 0, 0x18000
	v_add_u32_e32 v141, s55, v157
	s_add_i32 s56, 0, 0x1c000
	ds_read_b128 v[144:147], v141
	ds_read_b128 v[148:151], v141 offset:1024
	ds_read_b128 v[152:155], v141 offset:2048
	ds_read_b128 v[170:173], v141 offset:3072
	v_add_u32_e32 v141, s56, v157
	ds_read_b128 v[174:177], v141
	ds_read_b128 v[178:181], v141 offset:1024
	ds_read_b128 v[182:185], v141 offset:2048
	ds_read_b128 v[186:189], v141 offset:3072
	s_add_u32 s22, s22, 0x160000
	s_addc_u32 s23, s23, 0
	s_mov_b32 m0, s30
	v_lshl_add_u64 v[230:231], s[22:23], 0, v[128:129]
	ds_read_b128 v[190:193], v168 offset:32768
	ds_read_b128 v[194:197], v168 offset:33792
	ds_read_b128 v[198:201], v168 offset:34816
	ds_read_b128 v[202:205], v168 offset:35840
	ds_read_b128 v[206:209], v168 offset:36864
	ds_read_b128 v[210:213], v168 offset:37888
	ds_read_b128 v[214:217], v168 offset:38912
	ds_read_b128 v[218:221], v168 offset:39936
	global_load_lds_dwordx4 v[230:231], off
	v_lshl_add_u64 v[230:231], s[22:23], 0, v[132:133]
	s_mov_b32 m0, s31
	s_nop 0
	global_load_lds_dwordx4 v[230:231], off
	s_waitcnt vmcnt(8)
	s_waitcnt lgkmcnt(0)
	s_barrier
	s_waitcnt lgkmcnt(0)
	v_mfma_f32_16x16x32_bf16 v[124:127], v[144:147], v[190:193], v[124:127]
	v_mfma_f32_16x16x32_bf16 v[120:123], v[152:155], v[190:193], v[120:123]
	v_mfma_f32_16x16x32_bf16 v[116:119], v[144:147], v[198:201], v[116:119]
	v_mfma_f32_16x16x32_bf16 v[112:115], v[152:155], v[198:201], v[112:115]
	v_mfma_f32_16x16x32_bf16 v[108:111], v[144:147], v[206:209], v[108:111]
	v_mfma_f32_16x16x32_bf16 v[104:107], v[152:155], v[206:209], v[104:107]
	v_mfma_f32_16x16x32_bf16 v[100:103], v[144:147], v[214:217], v[100:103]
	v_mfma_f32_16x16x32_bf16 v[96:99], v[152:155], v[214:217], v[96:99]
	v_mfma_f32_16x16x32_bf16 v[124:127], v[148:151], v[194:197], v[124:127]
	v_mfma_f32_16x16x32_bf16 v[120:123], v[170:173], v[194:197], v[120:123]
	v_mfma_f32_16x16x32_bf16 v[116:119], v[148:151], v[202:205], v[116:119]
	v_mfma_f32_16x16x32_bf16 v[112:115], v[170:173], v[202:205], v[112:115]
	v_mfma_f32_16x16x32_bf16 v[108:111], v[148:151], v[210:213], v[108:111]
	v_mfma_f32_16x16x32_bf16 v[104:107], v[170:173], v[210:213], v[104:107]
	v_mfma_f32_16x16x32_bf16 v[100:103], v[148:151], v[218:221], v[100:103]
	v_mfma_f32_16x16x32_bf16 v[96:99], v[170:173], v[218:221], v[96:99]
	v_mfma_f32_16x16x32_bf16 v[68:71], v[174:177], v[190:193], v[68:71]
	v_mfma_f32_16x16x32_bf16 v[60:63], v[182:185], v[190:193], v[60:63]
	v_mfma_f32_16x16x32_bf16 v[52:55], v[174:177], v[198:201], v[52:55]
	v_mfma_f32_16x16x32_bf16 v[48:51], v[182:185], v[198:201], v[48:51]
	v_mfma_f32_16x16x32_bf16 v[44:47], v[174:177], v[206:209], v[44:47]
	v_mfma_f32_16x16x32_bf16 v[40:43], v[182:185], v[206:209], v[40:43]
	v_mfma_f32_16x16x32_bf16 v[36:39], v[174:177], v[214:217], v[36:39]
	v_mfma_f32_16x16x32_bf16 v[32:35], v[182:185], v[214:217], v[32:35]
	v_mfma_f32_16x16x32_bf16 v[68:71], v[178:181], v[194:197], v[68:71]
	v_mfma_f32_16x16x32_bf16 v[60:63], v[186:189], v[194:197], v[60:63]
	v_mfma_f32_16x16x32_bf16 v[52:55], v[178:181], v[202:205], v[52:55]
	v_mfma_f32_16x16x32_bf16 v[48:51], v[186:189], v[202:205], v[48:51]
	v_mfma_f32_16x16x32_bf16 v[44:47], v[178:181], v[210:213], v[44:47]
	v_mfma_f32_16x16x32_bf16 v[40:43], v[186:189], v[210:213], v[40:43]
	v_mfma_f32_16x16x32_bf16 v[36:39], v[178:181], v[218:221], v[36:39]
	v_mfma_f32_16x16x32_bf16 v[32:35], v[186:189], v[218:221], v[32:35]
	s_barrier
; #define PG8_STAGE(bufoff, gbase, voff) do { _Pragma("unroll") for (int _i = 0; _i < 2; ++_i) \
;         __builtin_amdgcn_global_load_lds((const unsigned*)((const char*)(gbase) + (voff)[_i]), (LAS unsigned*)(lds + (bufoff) + ldsw + _i * 8192), 16, 0, 0); } while (0)
; #define PG8_LDA(dst, b, h) do { _Pragma("unroll") for (int m = 0; m < 4; ++m) _Pragma("unroll") for (int k = 0; k < 2; ++k) dst[m][k] = *(const LAS bf16x8*)(lds + PG8_SA(b, h) + aoff + m * 2048 + k * 1024); } while (0)
; #define PG8_MMA(ai, bj, At, Bt) do { __builtin_amdgcn_s_setprio(1); _Pragma("unroll") for (int m = 0; m < 4; ++m) _Pragma("unroll") for (int n = 0; n < 2; ++n) _Pragma("unroll") for (int k = 0; k < 2; ++k) \
;         acc[ai][bj][m][n] = __builtin_amdgcn_mfma_f32_16x16x32_bf16(Bt[n][k], At[m][k], acc[ai][bj][m][n], 0, 0, 0); __builtin_amdgcn_s_setprio(0); } while (0)
; #define PG8_WAIT_V(n) asm volatile("s_waitcnt vmcnt(" #n ")" ::: "memory")
; #define PG8_WAIT_L(n) asm volatile("s_waitcnt lgkmcnt(" #n ")" ::: "memory")
; #define PG8_BAR __builtin_amdgcn_s_barrier()
; #define PG8_SCHED __builtin_amdgcn_sched_barrier(0)
; __device__ __forceinline__ void gemm_phase(LAS unsigned char* lds, const Params& p, const bf16_t* gA, const bf16_t* gBt, const int gM, const int gN, const int gK, const int epi, const int perm, bf16_t* const Hp, const int goff, const float coef) {
;     ...
;             PG8_LDA(At, 1, 1); PG8_STAGE(PG8_SB(1, 0), b3, voffB); PG8_STAGE(PG8_SB(1, 1), b3 + hstep, voffB); PG8_STAGE(PG8_SA(1, 0), a3, voffA);
;             PG8_WAIT_V(8); PG8_WAIT_L(0); PG8_BAR; PG8_MMA(1, 0, At, B0); PG8_MMA(1, 1, At, B1); PG8_BAR; PG8_SCHED;
;         }
;         if (wr == 0) PG8_BAR;
	s_add_i32 s22, s55, s27
	v_lshl_add_u64 v[222:223], v[222:223], 0, s[10:11]
	s_mov_b32 m0, s22
	ds_read_b128 v[190:193], v168 offset:49152
	ds_read_b128 v[194:197], v168 offset:50176
	ds_read_b128 v[198:201], v168 offset:51200
	ds_read_b128 v[202:205], v168 offset:52224
	ds_read_b128 v[206:209], v168 offset:53248
	ds_read_b128 v[210:213], v168 offset:54272
	ds_read_b128 v[214:217], v168 offset:55296
	ds_read_b128 v[218:221], v168 offset:56320
	global_load_lds_dwordx4 v[222:223], off
	s_add_i32 m0, s22, 0x2000
	s_add_u32 s20, s20, 0x160080
	v_lshl_add_u64 v[222:223], v[224:225], 0, s[10:11]
	s_addc_u32 s21, s21, 0
	s_add_i32 s22, s56, s27
	global_load_lds_dwordx4 v[222:223], off
	v_lshl_add_u64 v[222:223], s[20:21], 0, v[130:131]
	s_mov_b32 m0, s22
	s_nop 0
	global_load_lds_dwordx4 v[222:223], off
	v_lshl_add_u64 v[222:223], s[20:21], 0, v[134:135]
	s_add_i32 m0, s22, 0x2000
	s_nop 0
	global_load_lds_dwordx4 v[222:223], off
	v_lshl_add_u64 v[222:223], v[226:227], 0, s[10:11]
	s_mov_b32 m0, s36
	s_nop 0
	global_load_lds_dwordx4 v[222:223], off
	v_lshl_add_u64 v[222:223], v[228:229], 0, s[10:11]
	s_mov_b32 m0, s37
	s_nop 0
	global_load_lds_dwordx4 v[222:223], off
	s_waitcnt vmcnt(8)
	s_waitcnt lgkmcnt(0)
	s_barrier
	s_waitcnt lgkmcnt(0)
	v_mfma_f32_16x16x32_bf16 v[92:95], v[144:147], v[190:193], v[92:95]
	v_mfma_f32_16x16x32_bf16 v[88:91], v[152:155], v[190:193], v[88:91]
	v_mfma_f32_16x16x32_bf16 v[84:87], v[144:147], v[198:201], v[84:87]
	v_mfma_f32_16x16x32_bf16 v[80:83], v[152:155], v[198:201], v[80:83]
	v_mfma_f32_16x16x32_bf16 v[76:79], v[144:147], v[206:209], v[76:79]
	v_mfma_f32_16x16x32_bf16 v[72:75], v[152:155], v[206:209], v[72:75]
	v_mfma_f32_16x16x32_bf16 v[64:67], v[144:147], v[214:217], v[64:67]
	v_mfma_f32_16x16x32_bf16 v[56:59], v[152:155], v[214:217], v[56:59]
	v_mfma_f32_16x16x32_bf16 v[92:95], v[148:151], v[194:197], v[92:95]
	v_mfma_f32_16x16x32_bf16 v[88:91], v[170:173], v[194:197], v[88:91]
	v_mfma_f32_16x16x32_bf16 v[84:87], v[148:151], v[202:205], v[84:87]
	v_mfma_f32_16x16x32_bf16 v[80:83], v[170:173], v[202:205], v[80:83]
	v_mfma_f32_16x16x32_bf16 v[76:79], v[148:151], v[210:213], v[76:79]
	v_mfma_f32_16x16x32_bf16 v[72:75], v[170:173], v[210:213], v[72:75]
	v_mfma_f32_16x16x32_bf16 v[64:67], v[148:151], v[218:221], v[64:67]
	v_mfma_f32_16x16x32_bf16 v[56:59], v[170:173], v[218:221], v[56:59]
	v_mfma_f32_16x16x32_bf16 v[28:31], v[174:177], v[190:193], v[28:31]
	v_mfma_f32_16x16x32_bf16 v[24:27], v[182:185], v[190:193], v[24:27]
	v_mfma_f32_16x16x32_bf16 v[20:23], v[174:177], v[198:201], v[20:23]
	v_mfma_f32_16x16x32_bf16 v[16:19], v[182:185], v[198:201], v[16:19]
	v_mfma_f32_16x16x32_bf16 v[12:15], v[174:177], v[206:209], v[12:15]
	v_mfma_f32_16x16x32_bf16 v[8:11], v[182:185], v[206:209], v[8:11]
	v_mfma_f32_16x16x32_bf16 v[4:7], v[174:177], v[214:217], v[4:7]
	v_mfma_f32_16x16x32_bf16 v[0:3], v[182:185], v[214:217], v[0:3]
	v_mfma_f32_16x16x32_bf16 v[28:31], v[178:181], v[194:197], v[28:31]
	v_mfma_f32_16x16x32_bf16 v[24:27], v[186:189], v[194:197], v[24:27]
	v_mfma_f32_16x16x32_bf16 v[20:23], v[178:181], v[202:205], v[20:23]
	v_mfma_f32_16x16x32_bf16 v[16:19], v[186:189], v[202:205], v[16:19]
	v_mfma_f32_16x16x32_bf16 v[12:15], v[178:181], v[210:213], v[12:15]
	v_mfma_f32_16x16x32_bf16 v[8:11], v[186:189], v[210:213], v[8:11]
	v_mfma_f32_16x16x32_bf16 v[4:7], v[178:181], v[218:221], v[4:7]
	v_mfma_f32_16x16x32_bf16 v[0:3], v[186:189], v[218:221], v[0:3]
	s_barrier
	s_add_u32 s18, s18, 0x100
	s_addc_u32 s19, s19, 0
	s_add_u32 s52, s52, 0x100
	s_addc_u32 s53, s53, 0
	s_cmp_ge_u32 s54, s50
	s_mov_b32 s20, s54
	s_cbranch_scc0 .LBB0_1827
	s_and_b64 vcc, exec, s[12:13]
	s_cbranch_vccz .LBB0_1830
	s_barrier
